# best kernel + second K half cut 3,3(4),5,5 around the step barrier
# baseline (speedup 1.0000x reference)
.Lg2_ff2_loop17:
	s_add_u32 s58, s58, 0x800
	s_addc_u32 s59, s59, 0
	global_load_dwordx4 v[200:203], v160, s[58:59] offset:0
	global_load_dwordx4 v[204:207], v160, s[58:59] offset:1024
	global_load_dwordx4 v[208:211], v161, s[58:59] offset:0
	global_load_dwordx4 v[240:243], v161, s[58:59] offset:1024
	ds_read_b128 v[164:167], v156 offset:8192
	ds_read_b128 v[168:171], v156 offset:10240
	ds_read_b128 v[172:175], v156 offset:12288
	ds_read_b128 v[176:179], v156 offset:14336
	s_waitcnt lgkmcnt(4)
	v_mfma_f32_16x16x32_bf16 v[0:3], v[184:187], v[136:139], v[0:3]
	v_mfma_f32_16x16x32_bf16 v[4:7], v[192:195], v[136:139], v[4:7]
	v_mfma_f32_16x16x32_bf16 v[8:11], v[184:187], v[140:143], v[8:11]
	v_mfma_f32_16x16x32_bf16 v[12:15], v[192:195], v[140:143], v[12:15]
	v_mfma_f32_16x16x32_bf16 v[16:19], v[184:187], v[144:147], v[16:19]
	v_mfma_f32_16x16x32_bf16 v[20:23], v[192:195], v[144:147], v[20:23]
	v_mfma_f32_16x16x32_bf16 v[24:27], v[184:187], v[148:151], v[24:27]
	v_mfma_f32_16x16x32_bf16 v[28:31], v[192:195], v[148:151], v[28:31]
	ds_read_b128 v[136:139], v156 offset:16384
	ds_read_b128 v[140:143], v156 offset:18432
	ds_read_b128 v[144:147], v156 offset:20480
	ds_read_b128 v[148:151], v156 offset:22528
	s_waitcnt lgkmcnt(4)
	v_mfma_f32_16x16x32_bf16 v[32:35], v[184:187], v[164:167], v[32:35]
	v_mfma_f32_16x16x32_bf16 v[36:39], v[192:195], v[164:167], v[36:39]
	v_mfma_f32_16x16x32_bf16 v[40:43], v[184:187], v[168:171], v[40:43]
	v_mfma_f32_16x16x32_bf16 v[44:47], v[192:195], v[168:171], v[44:47]
	v_mfma_f32_16x16x32_bf16 v[48:51], v[184:187], v[172:175], v[48:51]
	v_mfma_f32_16x16x32_bf16 v[52:55], v[192:195], v[172:175], v[52:55]
	v_mfma_f32_16x16x32_bf16 v[56:59], v[184:187], v[176:179], v[56:59]
	v_mfma_f32_16x16x32_bf16 v[60:63], v[192:195], v[176:179], v[60:63]
	ds_read_b128 v[164:167], v156 offset:24576
	ds_read_b128 v[168:171], v156 offset:26624
	ds_read_b128 v[172:175], v156 offset:28672
	ds_read_b128 v[176:179], v156 offset:30720
	ds_read_b128 v[180:183], v156 offset:32768
	s_waitcnt lgkmcnt(5)
	v_mfma_f32_16x16x32_bf16 v[64:67], v[184:187], v[136:139], v[64:67]
	v_mfma_f32_16x16x32_bf16 v[68:71], v[192:195], v[136:139], v[68:71]
	v_mfma_f32_16x16x32_bf16 v[72:75], v[184:187], v[140:143], v[72:75]
	v_mfma_f32_16x16x32_bf16 v[76:79], v[192:195], v[140:143], v[76:79]
	v_mfma_f32_16x16x32_bf16 v[80:83], v[184:187], v[144:147], v[80:83]
	v_mfma_f32_16x16x32_bf16 v[84:87], v[192:195], v[144:147], v[84:87]
	v_mfma_f32_16x16x32_bf16 v[88:91], v[184:187], v[148:151], v[88:91]
	v_mfma_f32_16x16x32_bf16 v[92:95], v[192:195], v[148:151], v[92:95]
	ds_read_b128 v[136:139], v157 offset:0
	ds_read_b128 v[140:143], v157 offset:2048
	ds_read_b128 v[144:147], v157 offset:4096
	s_waitcnt lgkmcnt(3)
	v_mfma_f32_16x16x32_bf16 v[96:99], v[184:187], v[164:167], v[96:99]
	v_mfma_f32_16x16x32_bf16 v[100:103], v[192:195], v[164:167], v[100:103]
	v_mfma_f32_16x16x32_bf16 v[104:107], v[184:187], v[168:171], v[104:107]
	v_mfma_f32_16x16x32_bf16 v[108:111], v[192:195], v[168:171], v[108:111]
	v_mfma_f32_16x16x32_bf16 v[112:115], v[184:187], v[172:175], v[112:115]
	v_mfma_f32_16x16x32_bf16 v[116:119], v[192:195], v[172:175], v[116:119]
	v_mfma_f32_16x16x32_bf16 v[120:123], v[184:187], v[176:179], v[120:123]
	v_mfma_f32_16x16x32_bf16 v[124:127], v[192:195], v[176:179], v[124:127]
	v_mfma_f32_16x16x32_bf16 v[128:131], v[184:187], v[180:183], v[128:131]
	v_mfma_f32_16x16x32_bf16 v[132:135], v[192:195], v[180:183], v[132:135]
	ds_read_b128 v[164:167], v157 offset:6144
	ds_read_b128 v[168:171], v157 offset:8192
	ds_read_b128 v[172:175], v157 offset:10240
	ds_read_b128 v[176:179], v157 offset:12288
	s_waitcnt lgkmcnt(4)
	v_mfma_f32_16x16x32_bf16 v[0:3], v[188:191], v[136:139], v[0:3]
	v_mfma_f32_16x16x32_bf16 v[4:7], v[196:199], v[136:139], v[4:7]
	v_mfma_f32_16x16x32_bf16 v[8:11], v[188:191], v[140:143], v[8:11]
	v_mfma_f32_16x16x32_bf16 v[12:15], v[196:199], v[140:143], v[12:15]
	v_mfma_f32_16x16x32_bf16 v[16:19], v[188:191], v[144:147], v[16:19]
	v_mfma_f32_16x16x32_bf16 v[20:23], v[196:199], v[144:147], v[20:23]
	ds_read_b128 v[136:139], v157 offset:14336
	ds_read_b128 v[140:143], v157 offset:16384
	ds_read_b128 v[144:147], v157 offset:18432
	ds_read_b128 v[148:151], v157 offset:20480
	ds_read_b128 v[152:155], v157 offset:22528
	s_waitcnt lgkmcnt(5)
	v_mfma_f32_16x16x32_bf16 v[24:27], v[188:191], v[164:167], v[24:27]
	v_mfma_f32_16x16x32_bf16 v[28:31], v[196:199], v[164:167], v[28:31]
	v_mfma_f32_16x16x32_bf16 v[32:35], v[188:191], v[168:171], v[32:35]
	v_mfma_f32_16x16x32_bf16 v[36:39], v[196:199], v[168:171], v[36:39]
	v_mfma_f32_16x16x32_bf16 v[40:43], v[188:191], v[172:175], v[40:43]
	v_mfma_f32_16x16x32_bf16 v[44:47], v[196:199], v[172:175], v[44:47]
	v_mfma_f32_16x16x32_bf16 v[48:51], v[188:191], v[176:179], v[48:51]
	v_mfma_f32_16x16x32_bf16 v[52:55], v[196:199], v[176:179], v[52:55]
	ds_read_b128 v[164:167], v157 offset:24576
	ds_read_b128 v[168:171], v157 offset:26624
	ds_read_b128 v[172:175], v157 offset:28672
	ds_read_b128 v[176:179], v157 offset:30720
	ds_read_b128 v[180:183], v157 offset:32768
	s_waitcnt lgkmcnt(5)
	v_mfma_f32_16x16x32_bf16 v[56:59], v[188:191], v[136:139], v[56:59]
	v_mfma_f32_16x16x32_bf16 v[60:63], v[196:199], v[136:139], v[60:63]
	v_mfma_f32_16x16x32_bf16 v[64:67], v[188:191], v[140:143], v[64:67]
	v_mfma_f32_16x16x32_bf16 v[68:71], v[196:199], v[140:143], v[68:71]
	v_mfma_f32_16x16x32_bf16 v[72:75], v[188:191], v[144:147], v[72:75]
	v_mfma_f32_16x16x32_bf16 v[76:79], v[196:199], v[144:147], v[76:79]
	v_mfma_f32_16x16x32_bf16 v[80:83], v[188:191], v[148:151], v[80:83]
	v_mfma_f32_16x16x32_bf16 v[84:87], v[196:199], v[148:151], v[84:87]
	v_mfma_f32_16x16x32_bf16 v[88:91], v[188:191], v[152:155], v[88:91]
	v_mfma_f32_16x16x32_bf16 v[92:95], v[196:199], v[152:155], v[92:95]
	s_waitcnt vmcnt(0) lgkmcnt(0)
	s_barrier
	ds_read_b128 v[136:139], v158 offset:0
	ds_read_b128 v[140:143], v158 offset:2048
	ds_read_b128 v[144:147], v158 offset:4096
	ds_read_b128 v[148:151], v158 offset:6144
	s_cmp_ge_u32 s63, 62
	s_cbranch_scc1 .Lg2_ff2_nd17_0
	s_add_u32 s56, s56, 0x80
	s_addc_u32 s57, s57, 0
	s_add_u32 m0, s62, 0x0
	s_add_u32 s4, s56, 0x0
	s_addc_u32 s5, s57, 0
	global_load_lds_dwordx4 v162, s[4:5]
	s_add_u32 m0, s62, 0x1000
	s_add_u32 s4, s56, 0x40000
	s_addc_u32 s5, s57, 0
	global_load_lds_dwordx4 v162, s[4:5]
	s_add_u32 m0, s62, 0x2000
	s_add_u32 s4, s56, 0x80000
	s_addc_u32 s5, s57, 0
	global_load_lds_dwordx4 v162, s[4:5]
	s_add_u32 m0, s62, 0x3000
	s_add_u32 s4, s56, 0xc0000
	s_addc_u32 s5, s57, 0
	global_load_lds_dwordx4 v162, s[4:5]
	s_add_u32 m0, s62, 0x4000
	s_add_u32 s4, s56, 0x100000
	s_addc_u32 s5, s57, 0
	global_load_lds_dwordx4 v162, s[4:5]
	s_add_u32 m0, s62, 0x5000
	s_add_u32 s4, s56, 0x140000
	s_addc_u32 s5, s57, 0
	global_load_lds_dwordx4 v162, s[4:5]
	s_add_u32 m0, s62, 0x6000
	s_add_u32 s4, s56, 0x180000
	s_addc_u32 s5, s57, 0
	global_load_lds_dwordx4 v162, s[4:5]
	s_add_u32 m0, s62, 0x7000
	s_add_u32 s4, s56, 0x1c0000
	s_addc_u32 s5, s57, 0
	global_load_lds_dwordx4 v162, s[4:5]
	s_cmp_gt_u32 s70, 1
	s_cbranch_scc1 .Lg2_ff2_nodma_2
	s_add_u32 m0, s62, 0x8000
	s_add_u32 s4, s56, 0x200000
	s_addc_u32 s5, s57, 0
	global_load_lds_dwordx4 v162, s[4:5]

.Lg2_ff2_nb17_1:
	ds_read_b128 v[164:167], v158 offset:8192
	ds_read_b128 v[168:171], v158 offset:10240
	ds_read_b128 v[172:175], v158 offset:12288
	ds_read_b128 v[176:179], v158 offset:14336
	s_waitcnt lgkmcnt(4)
	v_mfma_f32_16x16x32_bf16 v[0:3], v[200:203], v[136:139], v[0:3]
	v_mfma_f32_16x16x32_bf16 v[4:7], v[208:211], v[136:139], v[4:7]
	v_mfma_f32_16x16x32_bf16 v[8:11], v[200:203], v[140:143], v[8:11]
	v_mfma_f32_16x16x32_bf16 v[12:15], v[208:211], v[140:143], v[12:15]
	v_mfma_f32_16x16x32_bf16 v[16:19], v[200:203], v[144:147], v[16:19]
	v_mfma_f32_16x16x32_bf16 v[20:23], v[208:211], v[144:147], v[20:23]
	v_mfma_f32_16x16x32_bf16 v[24:27], v[200:203], v[148:151], v[24:27]
	v_mfma_f32_16x16x32_bf16 v[28:31], v[208:211], v[148:151], v[28:31]
	ds_read_b128 v[136:139], v158 offset:16384
	ds_read_b128 v[140:143], v158 offset:18432
	ds_read_b128 v[144:147], v158 offset:20480
	ds_read_b128 v[148:151], v158 offset:22528
	s_waitcnt lgkmcnt(4)
	v_mfma_f32_16x16x32_bf16 v[32:35], v[200:203], v[164:167], v[32:35]
	v_mfma_f32_16x16x32_bf16 v[36:39], v[208:211], v[164:167], v[36:39]
	v_mfma_f32_16x16x32_bf16 v[40:43], v[200:203], v[168:171], v[40:43]
	v_mfma_f32_16x16x32_bf16 v[44:47], v[208:211], v[168:171], v[44:47]
	v_mfma_f32_16x16x32_bf16 v[48:51], v[200:203], v[172:175], v[48:51]
	v_mfma_f32_16x16x32_bf16 v[52:55], v[208:211], v[172:175], v[52:55]
	v_mfma_f32_16x16x32_bf16 v[56:59], v[200:203], v[176:179], v[56:59]
	v_mfma_f32_16x16x32_bf16 v[60:63], v[208:211], v[176:179], v[60:63]
	ds_read_b128 v[164:167], v158 offset:24576
	ds_read_b128 v[168:171], v158 offset:26624
	ds_read_b128 v[172:175], v158 offset:28672
	ds_read_b128 v[176:179], v158 offset:30720
	ds_read_b128 v[180:183], v158 offset:32768
	s_waitcnt lgkmcnt(5)
	v_mfma_f32_16x16x32_bf16 v[64:67], v[200:203], v[136:139], v[64:67]
	v_mfma_f32_16x16x32_bf16 v[68:71], v[208:211], v[136:139], v[68:71]
	v_mfma_f32_16x16x32_bf16 v[72:75], v[200:203], v[140:143], v[72:75]
	v_mfma_f32_16x16x32_bf16 v[76:79], v[208:211], v[140:143], v[76:79]
	v_mfma_f32_16x16x32_bf16 v[80:83], v[200:203], v[144:147], v[80:83]
	v_mfma_f32_16x16x32_bf16 v[84:87], v[208:211], v[144:147], v[84:87]
	v_mfma_f32_16x16x32_bf16 v[88:91], v[200:203], v[148:151], v[88:91]
	v_mfma_f32_16x16x32_bf16 v[92:95], v[208:211], v[148:151], v[92:95]
	ds_read_b128 v[136:139], v159 offset:0
	ds_read_b128 v[140:143], v159 offset:2048
	ds_read_b128 v[144:147], v159 offset:4096
	s_waitcnt lgkmcnt(3)
	v_mfma_f32_16x16x32_bf16 v[96:99], v[200:203], v[164:167], v[96:99]
	v_mfma_f32_16x16x32_bf16 v[100:103], v[208:211], v[164:167], v[100:103]
	v_mfma_f32_16x16x32_bf16 v[104:107], v[200:203], v[168:171], v[104:107]
	v_mfma_f32_16x16x32_bf16 v[108:111], v[208:211], v[168:171], v[108:111]
	v_mfma_f32_16x16x32_bf16 v[112:115], v[200:203], v[172:175], v[112:115]
	v_mfma_f32_16x16x32_bf16 v[116:119], v[208:211], v[172:175], v[116:119]
	v_mfma_f32_16x16x32_bf16 v[120:123], v[200:203], v[176:179], v[120:123]
	v_mfma_f32_16x16x32_bf16 v[124:127], v[208:211], v[176:179], v[124:127]
	v_mfma_f32_16x16x32_bf16 v[128:131], v[200:203], v[180:183], v[128:131]
	v_mfma_f32_16x16x32_bf16 v[132:135], v[208:211], v[180:183], v[132:135]
	ds_read_b128 v[164:167], v159 offset:6144
	ds_read_b128 v[168:171], v159 offset:8192
	ds_read_b128 v[172:175], v159 offset:10240
	ds_read_b128 v[176:179], v159 offset:12288
	s_waitcnt lgkmcnt(4)
	v_mfma_f32_16x16x32_bf16 v[0:3], v[204:207], v[136:139], v[0:3]
	v_mfma_f32_16x16x32_bf16 v[4:7], v[240:243], v[136:139], v[4:7]
	v_mfma_f32_16x16x32_bf16 v[8:11], v[204:207], v[140:143], v[8:11]
	v_mfma_f32_16x16x32_bf16 v[12:15], v[240:243], v[140:143], v[12:15]
	v_mfma_f32_16x16x32_bf16 v[16:19], v[204:207], v[144:147], v[16:19]
	v_mfma_f32_16x16x32_bf16 v[20:23], v[240:243], v[144:147], v[20:23]
	ds_read_b128 v[136:139], v159 offset:14336
	ds_read_b128 v[140:143], v159 offset:16384
	ds_read_b128 v[144:147], v159 offset:18432
	ds_read_b128 v[148:151], v159 offset:20480
	ds_read_b128 v[152:155], v159 offset:22528
	s_waitcnt lgkmcnt(5)
	v_mfma_f32_16x16x32_bf16 v[24:27], v[204:207], v[164:167], v[24:27]
	v_mfma_f32_16x16x32_bf16 v[28:31], v[240:243], v[164:167], v[28:31]
	v_mfma_f32_16x16x32_bf16 v[32:35], v[204:207], v[168:171], v[32:35]
	v_mfma_f32_16x16x32_bf16 v[36:39], v[240:243], v[168:171], v[36:39]
	v_mfma_f32_16x16x32_bf16 v[40:43], v[204:207], v[172:175], v[40:43]
	v_mfma_f32_16x16x32_bf16 v[44:47], v[240:243], v[172:175], v[44:47]
	v_mfma_f32_16x16x32_bf16 v[48:51], v[204:207], v[176:179], v[48:51]
	v_mfma_f32_16x16x32_bf16 v[52:55], v[240:243], v[176:179], v[52:55]
	ds_read_b128 v[164:167], v159 offset:24576
	ds_read_b128 v[168:171], v159 offset:26624
	ds_read_b128 v[172:175], v159 offset:28672
	ds_read_b128 v[176:179], v159 offset:30720
	ds_read_b128 v[180:183], v159 offset:32768
	s_waitcnt lgkmcnt(5)
	v_mfma_f32_16x16x32_bf16 v[56:59], v[204:207], v[136:139], v[56:59]
	v_mfma_f32_16x16x32_bf16 v[60:63], v[240:243], v[136:139], v[60:63]
	v_mfma_f32_16x16x32_bf16 v[64:67], v[204:207], v[140:143], v[64:67]
	v_mfma_f32_16x16x32_bf16 v[68:71], v[240:243], v[140:143], v[68:71]
	v_mfma_f32_16x16x32_bf16 v[72:75], v[204:207], v[144:147], v[72:75]
	v_mfma_f32_16x16x32_bf16 v[76:79], v[240:243], v[144:147], v[76:79]
	v_mfma_f32_16x16x32_bf16 v[80:83], v[204:207], v[148:151], v[80:83]
	v_mfma_f32_16x16x32_bf16 v[84:87], v[240:243], v[148:151], v[84:87]
	v_mfma_f32_16x16x32_bf16 v[88:91], v[204:207], v[152:155], v[88:91]
	v_mfma_f32_16x16x32_bf16 v[92:95], v[240:243], v[152:155], v[92:95]
	s_waitcnt vmcnt(0) lgkmcnt(0)
	s_barrier
	s_cmp_ge_u32 s63, 62
	s_cbranch_scc1 .Lg2_ff2_nd17_1
	ds_read_b128 v[136:139], v156 offset:0
	ds_read_b128 v[140:143], v156 offset:2048
	ds_read_b128 v[144:147], v156 offset:4096
	ds_read_b128 v[148:151], v156 offset:6144
	s_add_u32 s56, s56, 0x80
	s_addc_u32 s57, s57, 0
	s_add_u32 m0, s62, 0x8800
	s_add_u32 s4, s56, 0x0
	s_addc_u32 s5, s57, 0
	global_load_lds_dwordx4 v162, s[4:5]
	s_add_u32 m0, s62, 0x9800
	s_add_u32 s4, s56, 0x40000
	s_addc_u32 s5, s57, 0
	global_load_lds_dwordx4 v162, s[4:5]
	s_add_u32 m0, s62, 0xa800
	s_add_u32 s4, s56, 0x80000
	s_addc_u32 s5, s57, 0
	global_load_lds_dwordx4 v162, s[4:5]
	s_add_u32 m0, s62, 0xb800
	s_add_u32 s4, s56, 0xc0000
	s_addc_u32 s5, s57, 0
	global_load_lds_dwordx4 v162, s[4:5]
	s_add_u32 m0, s62, 0xc800
	s_add_u32 s4, s56, 0x100000
	s_addc_u32 s5, s57, 0
	global_load_lds_dwordx4 v162, s[4:5]
	s_add_u32 m0, s62, 0xd800
	s_add_u32 s4, s56, 0x140000
	s_addc_u32 s5, s57, 0
	global_load_lds_dwordx4 v162, s[4:5]
	s_add_u32 m0, s62, 0xe800
	s_add_u32 s4, s56, 0x180000
	s_addc_u32 s5, s57, 0
	global_load_lds_dwordx4 v162, s[4:5]
	s_add_u32 m0, s62, 0xf800
	s_add_u32 s4, s56, 0x1c0000
	s_addc_u32 s5, s57, 0
	global_load_lds_dwordx4 v162, s[4:5]
	s_cmp_gt_u32 s70, 1
	s_cbranch_scc1 .Lg2_ff2_nodma_3
	s_add_u32 m0, s62, 0x10800
	s_add_u32 s4, s56, 0x200000
	s_addc_u32 s5, s57, 0
	global_load_lds_dwordx4 v162, s[4:5]

.Lg2_ff2_loop16:
	s_add_u32 s58, s58, 0x800
	s_addc_u32 s59, s59, 0
	global_load_dwordx4 v[200:203], v160, s[58:59] offset:0
	global_load_dwordx4 v[204:207], v160, s[58:59] offset:1024
	global_load_dwordx4 v[208:211], v161, s[58:59] offset:0
	global_load_dwordx4 v[240:243], v161, s[58:59] offset:1024
	ds_read_b128 v[164:167], v156 offset:8192
	ds_read_b128 v[168:171], v156 offset:10240
	ds_read_b128 v[172:175], v156 offset:12288
	ds_read_b128 v[176:179], v156 offset:14336
	s_waitcnt lgkmcnt(4)
	v_mfma_f32_16x16x32_bf16 v[0:3], v[184:187], v[136:139], v[0:3]
	v_mfma_f32_16x16x32_bf16 v[4:7], v[192:195], v[136:139], v[4:7]
	v_mfma_f32_16x16x32_bf16 v[8:11], v[184:187], v[140:143], v[8:11]
	v_mfma_f32_16x16x32_bf16 v[12:15], v[192:195], v[140:143], v[12:15]
	v_mfma_f32_16x16x32_bf16 v[16:19], v[184:187], v[144:147], v[16:19]
	v_mfma_f32_16x16x32_bf16 v[20:23], v[192:195], v[144:147], v[20:23]
	v_mfma_f32_16x16x32_bf16 v[24:27], v[184:187], v[148:151], v[24:27]
	v_mfma_f32_16x16x32_bf16 v[28:31], v[192:195], v[148:151], v[28:31]
	ds_read_b128 v[136:139], v156 offset:16384
	ds_read_b128 v[140:143], v156 offset:18432
	ds_read_b128 v[144:147], v156 offset:20480
	ds_read_b128 v[148:151], v156 offset:22528
	s_waitcnt lgkmcnt(4)
	v_mfma_f32_16x16x32_bf16 v[32:35], v[184:187], v[164:167], v[32:35]
	v_mfma_f32_16x16x32_bf16 v[36:39], v[192:195], v[164:167], v[36:39]
	v_mfma_f32_16x16x32_bf16 v[40:43], v[184:187], v[168:171], v[40:43]
	v_mfma_f32_16x16x32_bf16 v[44:47], v[192:195], v[168:171], v[44:47]
	v_mfma_f32_16x16x32_bf16 v[48:51], v[184:187], v[172:175], v[48:51]
	v_mfma_f32_16x16x32_bf16 v[52:55], v[192:195], v[172:175], v[52:55]
	v_mfma_f32_16x16x32_bf16 v[56:59], v[184:187], v[176:179], v[56:59]
	v_mfma_f32_16x16x32_bf16 v[60:63], v[192:195], v[176:179], v[60:63]
	ds_read_b128 v[164:167], v156 offset:24576
	ds_read_b128 v[168:171], v156 offset:26624
	ds_read_b128 v[172:175], v156 offset:28672
	ds_read_b128 v[176:179], v156 offset:30720
	s_waitcnt lgkmcnt(4)
	v_mfma_f32_16x16x32_bf16 v[64:67], v[184:187], v[136:139], v[64:67]
	v_mfma_f32_16x16x32_bf16 v[68:71], v[192:195], v[136:139], v[68:71]
	v_mfma_f32_16x16x32_bf16 v[72:75], v[184:187], v[140:143], v[72:75]
	v_mfma_f32_16x16x32_bf16 v[76:79], v[192:195], v[140:143], v[76:79]
	v_mfma_f32_16x16x32_bf16 v[80:83], v[184:187], v[144:147], v[80:83]
	v_mfma_f32_16x16x32_bf16 v[84:87], v[192:195], v[144:147], v[84:87]
	v_mfma_f32_16x16x32_bf16 v[88:91], v[184:187], v[148:151], v[88:91]
	v_mfma_f32_16x16x32_bf16 v[92:95], v[192:195], v[148:151], v[92:95]
	ds_read_b128 v[136:139], v157 offset:0
	ds_read_b128 v[140:143], v157 offset:2048
	ds_read_b128 v[144:147], v157 offset:4096
	s_waitcnt lgkmcnt(3)
	v_mfma_f32_16x16x32_bf16 v[96:99], v[184:187], v[164:167], v[96:99]
	v_mfma_f32_16x16x32_bf16 v[100:103], v[192:195], v[164:167], v[100:103]
	v_mfma_f32_16x16x32_bf16 v[104:107], v[184:187], v[168:171], v[104:107]
	v_mfma_f32_16x16x32_bf16 v[108:111], v[192:195], v[168:171], v[108:111]
	v_mfma_f32_16x16x32_bf16 v[112:115], v[184:187], v[172:175], v[112:115]
	v_mfma_f32_16x16x32_bf16 v[116:119], v[192:195], v[172:175], v[116:119]
	v_mfma_f32_16x16x32_bf16 v[120:123], v[184:187], v[176:179], v[120:123]
	v_mfma_f32_16x16x32_bf16 v[124:127], v[192:195], v[176:179], v[124:127]
	ds_read_b128 v[164:167], v157 offset:6144
	ds_read_b128 v[168:171], v157 offset:8192
	ds_read_b128 v[172:175], v157 offset:10240
	s_waitcnt lgkmcnt(3)
	v_mfma_f32_16x16x32_bf16 v[0:3], v[188:191], v[136:139], v[0:3]
	v_mfma_f32_16x16x32_bf16 v[4:7], v[196:199], v[136:139], v[4:7]
	v_mfma_f32_16x16x32_bf16 v[8:11], v[188:191], v[140:143], v[8:11]
	v_mfma_f32_16x16x32_bf16 v[12:15], v[196:199], v[140:143], v[12:15]
	v_mfma_f32_16x16x32_bf16 v[16:19], v[188:191], v[144:147], v[16:19]
	v_mfma_f32_16x16x32_bf16 v[20:23], v[196:199], v[144:147], v[20:23]
	ds_read_b128 v[136:139], v157 offset:12288
	ds_read_b128 v[140:143], v157 offset:14336
	ds_read_b128 v[144:147], v157 offset:16384
	ds_read_b128 v[148:151], v157 offset:18432
	ds_read_b128 v[152:155], v157 offset:20480
	s_waitcnt lgkmcnt(5)
	v_mfma_f32_16x16x32_bf16 v[24:27], v[188:191], v[164:167], v[24:27]
	v_mfma_f32_16x16x32_bf16 v[28:31], v[196:199], v[164:167], v[28:31]
	v_mfma_f32_16x16x32_bf16 v[32:35], v[188:191], v[168:171], v[32:35]
	v_mfma_f32_16x16x32_bf16 v[36:39], v[196:199], v[168:171], v[36:39]
	v_mfma_f32_16x16x32_bf16 v[40:43], v[188:191], v[172:175], v[40:43]
	v_mfma_f32_16x16x32_bf16 v[44:47], v[196:199], v[172:175], v[44:47]
	ds_read_b128 v[164:167], v157 offset:22528
	ds_read_b128 v[168:171], v157 offset:24576
	ds_read_b128 v[172:175], v157 offset:26624
	ds_read_b128 v[176:179], v157 offset:28672
	ds_read_b128 v[180:183], v157 offset:30720
	s_waitcnt lgkmcnt(5)
	v_mfma_f32_16x16x32_bf16 v[48:51], v[188:191], v[136:139], v[48:51]
	v_mfma_f32_16x16x32_bf16 v[52:55], v[196:199], v[136:139], v[52:55]
	v_mfma_f32_16x16x32_bf16 v[56:59], v[188:191], v[140:143], v[56:59]
	v_mfma_f32_16x16x32_bf16 v[60:63], v[196:199], v[140:143], v[60:63]
	v_mfma_f32_16x16x32_bf16 v[64:67], v[188:191], v[144:147], v[64:67]
	v_mfma_f32_16x16x32_bf16 v[68:71], v[196:199], v[144:147], v[68:71]
	v_mfma_f32_16x16x32_bf16 v[72:75], v[188:191], v[148:151], v[72:75]
	v_mfma_f32_16x16x32_bf16 v[76:79], v[196:199], v[148:151], v[76:79]
	v_mfma_f32_16x16x32_bf16 v[80:83], v[188:191], v[152:155], v[80:83]
	v_mfma_f32_16x16x32_bf16 v[84:87], v[196:199], v[152:155], v[84:87]
	s_waitcnt vmcnt(0) lgkmcnt(0)
	s_barrier
	ds_read_b128 v[136:139], v158 offset:0
	ds_read_b128 v[140:143], v158 offset:2048
	ds_read_b128 v[144:147], v158 offset:4096
	ds_read_b128 v[148:151], v158 offset:6144
	s_cmp_ge_u32 s63, 62
	s_cbranch_scc1 .Lg2_ff2_nd16_0
	s_add_u32 s56, s56, 0x80
	s_addc_u32 s57, s57, 0
	s_add_u32 m0, s62, 0x0
	s_add_u32 s4, s56, 0x0
	s_addc_u32 s5, s57, 0
	global_load_lds_dwordx4 v162, s[4:5]
	s_add_u32 m0, s62, 0x1000
	s_add_u32 s4, s56, 0x40000
	s_addc_u32 s5, s57, 0
	global_load_lds_dwordx4 v162, s[4:5]
	s_add_u32 m0, s62, 0x2000
	s_add_u32 s4, s56, 0x80000
	s_addc_u32 s5, s57, 0
	global_load_lds_dwordx4 v162, s[4:5]
	s_add_u32 m0, s62, 0x3000
	s_add_u32 s4, s56, 0xc0000
	s_addc_u32 s5, s57, 0
	global_load_lds_dwordx4 v162, s[4:5]
	s_add_u32 m0, s62, 0x4000
	s_add_u32 s4, s56, 0x100000
	s_addc_u32 s5, s57, 0
	global_load_lds_dwordx4 v162, s[4:5]
	s_add_u32 m0, s62, 0x5000
	s_add_u32 s4, s56, 0x140000
	s_addc_u32 s5, s57, 0
	global_load_lds_dwordx4 v162, s[4:5]
	s_add_u32 m0, s62, 0x6000
	s_add_u32 s4, s56, 0x180000
	s_addc_u32 s5, s57, 0
	global_load_lds_dwordx4 v162, s[4:5]
	s_add_u32 m0, s62, 0x7000
	s_add_u32 s4, s56, 0x1c0000
	s_addc_u32 s5, s57, 0
	global_load_lds_dwordx4 v162, s[4:5]
.Lg2_ff2_nd16_0:
	v_mfma_f32_16x16x32_bf16 v[88:91], v[188:191], v[164:167], v[88:91]
	v_mfma_f32_16x16x32_bf16 v[92:95], v[196:199], v[164:167], v[92:95]
	v_mfma_f32_16x16x32_bf16 v[96:99], v[188:191], v[168:171], v[96:99]
	v_mfma_f32_16x16x32_bf16 v[100:103], v[196:199], v[168:171], v[100:103]
	v_mfma_f32_16x16x32_bf16 v[104:107], v[188:191], v[172:175], v[104:107]
	v_mfma_f32_16x16x32_bf16 v[108:111], v[196:199], v[172:175], v[108:111]
	v_mfma_f32_16x16x32_bf16 v[112:115], v[188:191], v[176:179], v[112:115]
	v_mfma_f32_16x16x32_bf16 v[116:119], v[196:199], v[176:179], v[116:119]
	v_mfma_f32_16x16x32_bf16 v[120:123], v[188:191], v[180:183], v[120:123]
	v_mfma_f32_16x16x32_bf16 v[124:127], v[196:199], v[180:183], v[124:127]
	s_cmp_ge_u32 s63, 62
	s_cbranch_scc1 .Lg2_ff2_nb16_1
	s_add_u32 s58, s58, 0x800
	s_addc_u32 s59, s59, 0
	global_load_dwordx4 v[184:187], v160, s[58:59] offset:0
	global_load_dwordx4 v[188:191], v160, s[58:59] offset:1024
	global_load_dwordx4 v[192:195], v161, s[58:59] offset:0
	global_load_dwordx4 v[196:199], v161, s[58:59] offset:1024
.Lg2_ff2_nb16_1:
	ds_read_b128 v[164:167], v158 offset:8192
	ds_read_b128 v[168:171], v158 offset:10240
	ds_read_b128 v[172:175], v158 offset:12288
	ds_read_b128 v[176:179], v158 offset:14336
	s_waitcnt lgkmcnt(4)
	v_mfma_f32_16x16x32_bf16 v[0:3], v[200:203], v[136:139], v[0:3]
	v_mfma_f32_16x16x32_bf16 v[4:7], v[208:211], v[136:139], v[4:7]
	v_mfma_f32_16x16x32_bf16 v[8:11], v[200:203], v[140:143], v[8:11]
	v_mfma_f32_16x16x32_bf16 v[12:15], v[208:211], v[140:143], v[12:15]
	v_mfma_f32_16x16x32_bf16 v[16:19], v[200:203], v[144:147], v[16:19]
	v_mfma_f32_16x16x32_bf16 v[20:23], v[208:211], v[144:147], v[20:23]
	v_mfma_f32_16x16x32_bf16 v[24:27], v[200:203], v[148:151], v[24:27]
	v_mfma_f32_16x16x32_bf16 v[28:31], v[208:211], v[148:151], v[28:31]
	ds_read_b128 v[136:139], v158 offset:16384
	ds_read_b128 v[140:143], v158 offset:18432
	ds_read_b128 v[144:147], v158 offset:20480
	ds_read_b128 v[148:151], v158 offset:22528
	s_waitcnt lgkmcnt(4)
	v_mfma_f32_16x16x32_bf16 v[32:35], v[200:203], v[164:167], v[32:35]
	v_mfma_f32_16x16x32_bf16 v[36:39], v[208:211], v[164:167], v[36:39]
	v_mfma_f32_16x16x32_bf16 v[40:43], v[200:203], v[168:171], v[40:43]
	v_mfma_f32_16x16x32_bf16 v[44:47], v[208:211], v[168:171], v[44:47]
	v_mfma_f32_16x16x32_bf16 v[48:51], v[200:203], v[172:175], v[48:51]
	v_mfma_f32_16x16x32_bf16 v[52:55], v[208:211], v[172:175], v[52:55]
	v_mfma_f32_16x16x32_bf16 v[56:59], v[200:203], v[176:179], v[56:59]
	v_mfma_f32_16x16x32_bf16 v[60:63], v[208:211], v[176:179], v[60:63]
	ds_read_b128 v[164:167], v158 offset:24576
	ds_read_b128 v[168:171], v158 offset:26624
	ds_read_b128 v[172:175], v158 offset:28672
	ds_read_b128 v[176:179], v158 offset:30720
	s_waitcnt lgkmcnt(4)
	v_mfma_f32_16x16x32_bf16 v[64:67], v[200:203], v[136:139], v[64:67]
	v_mfma_f32_16x16x32_bf16 v[68:71], v[208:211], v[136:139], v[68:71]
	v_mfma_f32_16x16x32_bf16 v[72:75], v[200:203], v[140:143], v[72:75]
	v_mfma_f32_16x16x32_bf16 v[76:79], v[208:211], v[140:143], v[76:79]
	v_mfma_f32_16x16x32_bf16 v[80:83], v[200:203], v[144:147], v[80:83]
	v_mfma_f32_16x16x32_bf16 v[84:87], v[208:211], v[144:147], v[84:87]
	v_mfma_f32_16x16x32_bf16 v[88:91], v[200:203], v[148:151], v[88:91]
	v_mfma_f32_16x16x32_bf16 v[92:95], v[208:211], v[148:151], v[92:95]
	ds_read_b128 v[136:139], v159 offset:0
	ds_read_b128 v[140:143], v159 offset:2048
	ds_read_b128 v[144:147], v159 offset:4096
	s_waitcnt lgkmcnt(3)
	v_mfma_f32_16x16x32_bf16 v[96:99], v[200:203], v[164:167], v[96:99]
	v_mfma_f32_16x16x32_bf16 v[100:103], v[208:211], v[164:167], v[100:103]
	v_mfma_f32_16x16x32_bf16 v[104:107], v[200:203], v[168:171], v[104:107]
	v_mfma_f32_16x16x32_bf16 v[108:111], v[208:211], v[168:171], v[108:111]
	v_mfma_f32_16x16x32_bf16 v[112:115], v[200:203], v[172:175], v[112:115]
	v_mfma_f32_16x16x32_bf16 v[116:119], v[208:211], v[172:175], v[116:119]
	v_mfma_f32_16x16x32_bf16 v[120:123], v[200:203], v[176:179], v[120:123]
	v_mfma_f32_16x16x32_bf16 v[124:127], v[208:211], v[176:179], v[124:127]
	ds_read_b128 v[164:167], v159 offset:6144
	ds_read_b128 v[168:171], v159 offset:8192
	ds_read_b128 v[172:175], v159 offset:10240
	s_waitcnt lgkmcnt(3)
	v_mfma_f32_16x16x32_bf16 v[0:3], v[204:207], v[136:139], v[0:3]
	v_mfma_f32_16x16x32_bf16 v[4:7], v[240:243], v[136:139], v[4:7]
	v_mfma_f32_16x16x32_bf16 v[8:11], v[204:207], v[140:143], v[8:11]
	v_mfma_f32_16x16x32_bf16 v[12:15], v[240:243], v[140:143], v[12:15]
	v_mfma_f32_16x16x32_bf16 v[16:19], v[204:207], v[144:147], v[16:19]
	v_mfma_f32_16x16x32_bf16 v[20:23], v[240:243], v[144:147], v[20:23]
	ds_read_b128 v[136:139], v159 offset:12288
	ds_read_b128 v[140:143], v159 offset:14336
	ds_read_b128 v[144:147], v159 offset:16384
	ds_read_b128 v[148:151], v159 offset:18432
	ds_read_b128 v[152:155], v159 offset:20480
	s_waitcnt lgkmcnt(5)
	v_mfma_f32_16x16x32_bf16 v[24:27], v[204:207], v[164:167], v[24:27]
	v_mfma_f32_16x16x32_bf16 v[28:31], v[240:243], v[164:167], v[28:31]
	v_mfma_f32_16x16x32_bf16 v[32:35], v[204:207], v[168:171], v[32:35]
	v_mfma_f32_16x16x32_bf16 v[36:39], v[240:243], v[168:171], v[36:39]
	v_mfma_f32_16x16x32_bf16 v[40:43], v[204:207], v[172:175], v[40:43]
	v_mfma_f32_16x16x32_bf16 v[44:47], v[240:243], v[172:175], v[44:47]
	ds_read_b128 v[164:167], v159 offset:22528
	ds_read_b128 v[168:171], v159 offset:24576
	ds_read_b128 v[172:175], v159 offset:26624
	ds_read_b128 v[176:179], v159 offset:28672
	ds_read_b128 v[180:183], v159 offset:30720
	s_waitcnt lgkmcnt(5)
	v_mfma_f32_16x16x32_bf16 v[48:51], v[204:207], v[136:139], v[48:51]
	v_mfma_f32_16x16x32_bf16 v[52:55], v[240:243], v[136:139], v[52:55]
	v_mfma_f32_16x16x32_bf16 v[56:59], v[204:207], v[140:143], v[56:59]
	v_mfma_f32_16x16x32_bf16 v[60:63], v[240:243], v[140:143], v[60:63]
	v_mfma_f32_16x16x32_bf16 v[64:67], v[204:207], v[144:147], v[64:67]
	v_mfma_f32_16x16x32_bf16 v[68:71], v[240:243], v[144:147], v[68:71]
	v_mfma_f32_16x16x32_bf16 v[72:75], v[204:207], v[148:151], v[72:75]
	v_mfma_f32_16x16x32_bf16 v[76:79], v[240:243], v[148:151], v[76:79]
	v_mfma_f32_16x16x32_bf16 v[80:83], v[204:207], v[152:155], v[80:83]
	v_mfma_f32_16x16x32_bf16 v[84:87], v[240:243], v[152:155], v[84:87]
	s_waitcnt vmcnt(0) lgkmcnt(0)
	s_barrier
	s_cmp_ge_u32 s63, 62
	s_cbranch_scc1 .Lg2_ff2_nd16_1
	ds_read_b128 v[136:139], v156 offset:0
	ds_read_b128 v[140:143], v156 offset:2048
	ds_read_b128 v[144:147], v156 offset:4096
	ds_read_b128 v[148:151], v156 offset:6144
	s_add_u32 s56, s56, 0x80
	s_addc_u32 s57, s57, 0
	s_add_u32 m0, s62, 0x8800
	s_add_u32 s4, s56, 0x0
	s_addc_u32 s5, s57, 0
	global_load_lds_dwordx4 v162, s[4:5]
	s_add_u32 m0, s62, 0x9800
	s_add_u32 s4, s56, 0x40000
	s_addc_u32 s5, s57, 0
	global_load_lds_dwordx4 v162, s[4:5]
	s_add_u32 m0, s62, 0xa800
	s_add_u32 s4, s56, 0x80000
	s_addc_u32 s5, s57, 0
	global_load_lds_dwordx4 v162, s[4:5]
	s_add_u32 m0, s62, 0xb800
	s_add_u32 s4, s56, 0xc0000
	s_addc_u32 s5, s57, 0
	global_load_lds_dwordx4 v162, s[4:5]
	s_add_u32 m0, s62, 0xc800
	s_add_u32 s4, s56, 0x100000
	s_addc_u32 s5, s57, 0
	global_load_lds_dwordx4 v162, s[4:5]
	s_add_u32 m0, s62, 0xd800
	s_add_u32 s4, s56, 0x140000
	s_addc_u32 s5, s57, 0
	global_load_lds_dwordx4 v162, s[4:5]
	s_add_u32 m0, s62, 0xe800
	s_add_u32 s4, s56, 0x180000
	s_addc_u32 s5, s57, 0
	global_load_lds_dwordx4 v162, s[4:5]
	s_add_u32 m0, s62, 0xf800
	s_add_u32 s4, s56, 0x1c0000
	s_addc_u32 s5, s57, 0
	global_load_lds_dwordx4 v162, s[4:5]

.Lg2_ff1_loop17:
	s_add_u32 s58, s58, 0x800
	s_addc_u32 s59, s59, 0
	global_load_dwordx4 v[200:203], v160, s[58:59] offset:0
	global_load_dwordx4 v[204:207], v160, s[58:59] offset:1024
	global_load_dwordx4 v[208:211], v161, s[58:59] offset:0
	global_load_dwordx4 v[240:243], v161, s[58:59] offset:1024
	ds_read_b128 v[164:167], v156 offset:8192
	ds_read_b128 v[168:171], v156 offset:10240
	ds_read_b128 v[172:175], v156 offset:12288
	ds_read_b128 v[176:179], v156 offset:14336
	s_waitcnt lgkmcnt(4)
	v_mfma_f32_16x16x32_bf16 v[0:3], v[184:187], v[136:139], v[0:3]
	v_mfma_f32_16x16x32_bf16 v[4:7], v[192:195], v[136:139], v[4:7]
	v_mfma_f32_16x16x32_bf16 v[8:11], v[184:187], v[140:143], v[8:11]
	v_mfma_f32_16x16x32_bf16 v[12:15], v[192:195], v[140:143], v[12:15]
	v_mfma_f32_16x16x32_bf16 v[16:19], v[184:187], v[144:147], v[16:19]
	v_mfma_f32_16x16x32_bf16 v[20:23], v[192:195], v[144:147], v[20:23]
	v_mfma_f32_16x16x32_bf16 v[24:27], v[184:187], v[148:151], v[24:27]
	v_mfma_f32_16x16x32_bf16 v[28:31], v[192:195], v[148:151], v[28:31]
	ds_read_b128 v[136:139], v156 offset:16384
	ds_read_b128 v[140:143], v156 offset:18432
	ds_read_b128 v[144:147], v156 offset:20480
	ds_read_b128 v[148:151], v156 offset:22528
	s_waitcnt lgkmcnt(4)
	v_mfma_f32_16x16x32_bf16 v[32:35], v[184:187], v[164:167], v[32:35]
	v_mfma_f32_16x16x32_bf16 v[36:39], v[192:195], v[164:167], v[36:39]
	v_mfma_f32_16x16x32_bf16 v[40:43], v[184:187], v[168:171], v[40:43]
	v_mfma_f32_16x16x32_bf16 v[44:47], v[192:195], v[168:171], v[44:47]
	v_mfma_f32_16x16x32_bf16 v[48:51], v[184:187], v[172:175], v[48:51]
	v_mfma_f32_16x16x32_bf16 v[52:55], v[192:195], v[172:175], v[52:55]
	v_mfma_f32_16x16x32_bf16 v[56:59], v[184:187], v[176:179], v[56:59]
	v_mfma_f32_16x16x32_bf16 v[60:63], v[192:195], v[176:179], v[60:63]
	ds_read_b128 v[164:167], v156 offset:24576
	ds_read_b128 v[168:171], v156 offset:26624
	ds_read_b128 v[172:175], v156 offset:28672
	ds_read_b128 v[176:179], v156 offset:30720
	ds_read_b128 v[180:183], v156 offset:32768
	s_waitcnt lgkmcnt(5)
	v_mfma_f32_16x16x32_bf16 v[64:67], v[184:187], v[136:139], v[64:67]
	v_mfma_f32_16x16x32_bf16 v[68:71], v[192:195], v[136:139], v[68:71]
	v_mfma_f32_16x16x32_bf16 v[72:75], v[184:187], v[140:143], v[72:75]
	v_mfma_f32_16x16x32_bf16 v[76:79], v[192:195], v[140:143], v[76:79]
	v_mfma_f32_16x16x32_bf16 v[80:83], v[184:187], v[144:147], v[80:83]
	v_mfma_f32_16x16x32_bf16 v[84:87], v[192:195], v[144:147], v[84:87]
	v_mfma_f32_16x16x32_bf16 v[88:91], v[184:187], v[148:151], v[88:91]
	v_mfma_f32_16x16x32_bf16 v[92:95], v[192:195], v[148:151], v[92:95]
	ds_read_b128 v[136:139], v157 offset:0
	ds_read_b128 v[140:143], v157 offset:2048
	ds_read_b128 v[144:147], v157 offset:4096
	s_waitcnt lgkmcnt(3)
	v_mfma_f32_16x16x32_bf16 v[96:99], v[184:187], v[164:167], v[96:99]
	v_mfma_f32_16x16x32_bf16 v[100:103], v[192:195], v[164:167], v[100:103]
	v_mfma_f32_16x16x32_bf16 v[104:107], v[184:187], v[168:171], v[104:107]
	v_mfma_f32_16x16x32_bf16 v[108:111], v[192:195], v[168:171], v[108:111]
	v_mfma_f32_16x16x32_bf16 v[112:115], v[184:187], v[172:175], v[112:115]
	v_mfma_f32_16x16x32_bf16 v[116:119], v[192:195], v[172:175], v[116:119]
	v_mfma_f32_16x16x32_bf16 v[120:123], v[184:187], v[176:179], v[120:123]
	v_mfma_f32_16x16x32_bf16 v[124:127], v[192:195], v[176:179], v[124:127]
	v_mfma_f32_16x16x32_bf16 v[128:131], v[184:187], v[180:183], v[128:131]
	v_mfma_f32_16x16x32_bf16 v[132:135], v[192:195], v[180:183], v[132:135]
	ds_read_b128 v[164:167], v157 offset:6144
	ds_read_b128 v[168:171], v157 offset:8192
	ds_read_b128 v[172:175], v157 offset:10240
	ds_read_b128 v[176:179], v157 offset:12288
	s_waitcnt lgkmcnt(4)
	v_mfma_f32_16x16x32_bf16 v[0:3], v[188:191], v[136:139], v[0:3]
	v_mfma_f32_16x16x32_bf16 v[4:7], v[196:199], v[136:139], v[4:7]
	v_mfma_f32_16x16x32_bf16 v[8:11], v[188:191], v[140:143], v[8:11]
	v_mfma_f32_16x16x32_bf16 v[12:15], v[196:199], v[140:143], v[12:15]
	v_mfma_f32_16x16x32_bf16 v[16:19], v[188:191], v[144:147], v[16:19]
	v_mfma_f32_16x16x32_bf16 v[20:23], v[196:199], v[144:147], v[20:23]
	ds_read_b128 v[136:139], v157 offset:14336
	ds_read_b128 v[140:143], v157 offset:16384
	ds_read_b128 v[144:147], v157 offset:18432
	ds_read_b128 v[148:151], v157 offset:20480
	ds_read_b128 v[152:155], v157 offset:22528
	s_waitcnt lgkmcnt(5)
	v_mfma_f32_16x16x32_bf16 v[24:27], v[188:191], v[164:167], v[24:27]
	v_mfma_f32_16x16x32_bf16 v[28:31], v[196:199], v[164:167], v[28:31]
	v_mfma_f32_16x16x32_bf16 v[32:35], v[188:191], v[168:171], v[32:35]
	v_mfma_f32_16x16x32_bf16 v[36:39], v[196:199], v[168:171], v[36:39]
	v_mfma_f32_16x16x32_bf16 v[40:43], v[188:191], v[172:175], v[40:43]
	v_mfma_f32_16x16x32_bf16 v[44:47], v[196:199], v[172:175], v[44:47]
	v_mfma_f32_16x16x32_bf16 v[48:51], v[188:191], v[176:179], v[48:51]
	v_mfma_f32_16x16x32_bf16 v[52:55], v[196:199], v[176:179], v[52:55]
	ds_read_b128 v[164:167], v157 offset:24576
	ds_read_b128 v[168:171], v157 offset:26624
	ds_read_b128 v[172:175], v157 offset:28672
	ds_read_b128 v[176:179], v157 offset:30720
	ds_read_b128 v[180:183], v157 offset:32768
	s_waitcnt lgkmcnt(5)
	v_mfma_f32_16x16x32_bf16 v[56:59], v[188:191], v[136:139], v[56:59]
	v_mfma_f32_16x16x32_bf16 v[60:63], v[196:199], v[136:139], v[60:63]
	v_mfma_f32_16x16x32_bf16 v[64:67], v[188:191], v[140:143], v[64:67]
	v_mfma_f32_16x16x32_bf16 v[68:71], v[196:199], v[140:143], v[68:71]
	v_mfma_f32_16x16x32_bf16 v[72:75], v[188:191], v[144:147], v[72:75]
	v_mfma_f32_16x16x32_bf16 v[76:79], v[196:199], v[144:147], v[76:79]
	v_mfma_f32_16x16x32_bf16 v[80:83], v[188:191], v[148:151], v[80:83]
	v_mfma_f32_16x16x32_bf16 v[84:87], v[196:199], v[148:151], v[84:87]
	v_mfma_f32_16x16x32_bf16 v[88:91], v[188:191], v[152:155], v[88:91]
	v_mfma_f32_16x16x32_bf16 v[92:95], v[196:199], v[152:155], v[92:95]
	s_waitcnt vmcnt(0) lgkmcnt(0)
	s_barrier
	ds_read_b128 v[136:139], v158 offset:0
	ds_read_b128 v[140:143], v158 offset:2048
	ds_read_b128 v[144:147], v158 offset:4096
	ds_read_b128 v[148:151], v158 offset:6144
	s_cmp_ge_u32 s63, 14
	s_cbranch_scc1 .Lg2_ff1_nd17_0
	s_add_u32 s56, s56, 0x80
	s_addc_u32 s57, s57, 0
	s_add_u32 m0, s62, 0x0
	s_add_u32 s4, s56, 0x0
	s_addc_u32 s5, s57, 0
	global_load_lds_dwordx4 v162, s[4:5]
	s_add_u32 m0, s62, 0x1000
	s_add_u32 s4, s56, 0x10000
	s_addc_u32 s5, s57, 0
	global_load_lds_dwordx4 v162, s[4:5]
	s_add_u32 m0, s62, 0x2000
	s_add_u32 s4, s56, 0x20000
	s_addc_u32 s5, s57, 0
	global_load_lds_dwordx4 v162, s[4:5]
	s_add_u32 m0, s62, 0x3000
	s_add_u32 s4, s56, 0x30000
	s_addc_u32 s5, s57, 0
	global_load_lds_dwordx4 v162, s[4:5]
	s_add_u32 m0, s62, 0x4000
	s_add_u32 s4, s56, 0x40000
	s_addc_u32 s5, s57, 0
	global_load_lds_dwordx4 v162, s[4:5]
	s_add_u32 m0, s62, 0x5000
	s_add_u32 s4, s56, 0x50000
	s_addc_u32 s5, s57, 0
	global_load_lds_dwordx4 v162, s[4:5]
	s_add_u32 m0, s62, 0x6000
	s_add_u32 s4, s56, 0x60000
	s_addc_u32 s5, s57, 0
	global_load_lds_dwordx4 v162, s[4:5]
	s_add_u32 m0, s62, 0x7000
	s_add_u32 s4, s56, 0x70000
	s_addc_u32 s5, s57, 0
	global_load_lds_dwordx4 v162, s[4:5]
	s_cmp_gt_u32 s70, 1
	s_cbranch_scc1 .Lg2_ff1_nodma_2
	s_add_u32 m0, s62, 0x8000
	s_add_u32 s4, s56, 0x80000
	s_addc_u32 s5, s57, 0
	global_load_lds_dwordx4 v162, s[4:5]

.Lg2_ff1_nb17_1:
	ds_read_b128 v[164:167], v158 offset:8192
	ds_read_b128 v[168:171], v158 offset:10240
	ds_read_b128 v[172:175], v158 offset:12288
	ds_read_b128 v[176:179], v158 offset:14336
	s_waitcnt lgkmcnt(4)
	v_mfma_f32_16x16x32_bf16 v[0:3], v[200:203], v[136:139], v[0:3]
	v_mfma_f32_16x16x32_bf16 v[4:7], v[208:211], v[136:139], v[4:7]
	v_mfma_f32_16x16x32_bf16 v[8:11], v[200:203], v[140:143], v[8:11]
	v_mfma_f32_16x16x32_bf16 v[12:15], v[208:211], v[140:143], v[12:15]
	v_mfma_f32_16x16x32_bf16 v[16:19], v[200:203], v[144:147], v[16:19]
	v_mfma_f32_16x16x32_bf16 v[20:23], v[208:211], v[144:147], v[20:23]
	v_mfma_f32_16x16x32_bf16 v[24:27], v[200:203], v[148:151], v[24:27]
	v_mfma_f32_16x16x32_bf16 v[28:31], v[208:211], v[148:151], v[28:31]
	ds_read_b128 v[136:139], v158 offset:16384
	ds_read_b128 v[140:143], v158 offset:18432
	ds_read_b128 v[144:147], v158 offset:20480
	ds_read_b128 v[148:151], v158 offset:22528
	s_waitcnt lgkmcnt(4)
	v_mfma_f32_16x16x32_bf16 v[32:35], v[200:203], v[164:167], v[32:35]
	v_mfma_f32_16x16x32_bf16 v[36:39], v[208:211], v[164:167], v[36:39]
	v_mfma_f32_16x16x32_bf16 v[40:43], v[200:203], v[168:171], v[40:43]
	v_mfma_f32_16x16x32_bf16 v[44:47], v[208:211], v[168:171], v[44:47]
	v_mfma_f32_16x16x32_bf16 v[48:51], v[200:203], v[172:175], v[48:51]
	v_mfma_f32_16x16x32_bf16 v[52:55], v[208:211], v[172:175], v[52:55]
	v_mfma_f32_16x16x32_bf16 v[56:59], v[200:203], v[176:179], v[56:59]
	v_mfma_f32_16x16x32_bf16 v[60:63], v[208:211], v[176:179], v[60:63]
	ds_read_b128 v[164:167], v158 offset:24576
	ds_read_b128 v[168:171], v158 offset:26624
	ds_read_b128 v[172:175], v158 offset:28672
	ds_read_b128 v[176:179], v158 offset:30720
	ds_read_b128 v[180:183], v158 offset:32768
	s_waitcnt lgkmcnt(5)
	v_mfma_f32_16x16x32_bf16 v[64:67], v[200:203], v[136:139], v[64:67]
	v_mfma_f32_16x16x32_bf16 v[68:71], v[208:211], v[136:139], v[68:71]
	v_mfma_f32_16x16x32_bf16 v[72:75], v[200:203], v[140:143], v[72:75]
	v_mfma_f32_16x16x32_bf16 v[76:79], v[208:211], v[140:143], v[76:79]
	v_mfma_f32_16x16x32_bf16 v[80:83], v[200:203], v[144:147], v[80:83]
	v_mfma_f32_16x16x32_bf16 v[84:87], v[208:211], v[144:147], v[84:87]
	v_mfma_f32_16x16x32_bf16 v[88:91], v[200:203], v[148:151], v[88:91]
	v_mfma_f32_16x16x32_bf16 v[92:95], v[208:211], v[148:151], v[92:95]
	ds_read_b128 v[136:139], v159 offset:0
	ds_read_b128 v[140:143], v159 offset:2048
	ds_read_b128 v[144:147], v159 offset:4096
	s_waitcnt lgkmcnt(3)
	v_mfma_f32_16x16x32_bf16 v[96:99], v[200:203], v[164:167], v[96:99]
	v_mfma_f32_16x16x32_bf16 v[100:103], v[208:211], v[164:167], v[100:103]
	v_mfma_f32_16x16x32_bf16 v[104:107], v[200:203], v[168:171], v[104:107]
	v_mfma_f32_16x16x32_bf16 v[108:111], v[208:211], v[168:171], v[108:111]
	v_mfma_f32_16x16x32_bf16 v[112:115], v[200:203], v[172:175], v[112:115]
	v_mfma_f32_16x16x32_bf16 v[116:119], v[208:211], v[172:175], v[116:119]
	v_mfma_f32_16x16x32_bf16 v[120:123], v[200:203], v[176:179], v[120:123]
	v_mfma_f32_16x16x32_bf16 v[124:127], v[208:211], v[176:179], v[124:127]
	v_mfma_f32_16x16x32_bf16 v[128:131], v[200:203], v[180:183], v[128:131]
	v_mfma_f32_16x16x32_bf16 v[132:135], v[208:211], v[180:183], v[132:135]
	ds_read_b128 v[164:167], v159 offset:6144
	ds_read_b128 v[168:171], v159 offset:8192
	ds_read_b128 v[172:175], v159 offset:10240
	ds_read_b128 v[176:179], v159 offset:12288
	s_waitcnt lgkmcnt(4)
	v_mfma_f32_16x16x32_bf16 v[0:3], v[204:207], v[136:139], v[0:3]
	v_mfma_f32_16x16x32_bf16 v[4:7], v[240:243], v[136:139], v[4:7]
	v_mfma_f32_16x16x32_bf16 v[8:11], v[204:207], v[140:143], v[8:11]
	v_mfma_f32_16x16x32_bf16 v[12:15], v[240:243], v[140:143], v[12:15]
	v_mfma_f32_16x16x32_bf16 v[16:19], v[204:207], v[144:147], v[16:19]
	v_mfma_f32_16x16x32_bf16 v[20:23], v[240:243], v[144:147], v[20:23]
	ds_read_b128 v[136:139], v159 offset:14336
	ds_read_b128 v[140:143], v159 offset:16384
	ds_read_b128 v[144:147], v159 offset:18432
	ds_read_b128 v[148:151], v159 offset:20480
	ds_read_b128 v[152:155], v159 offset:22528
	s_waitcnt lgkmcnt(5)
	v_mfma_f32_16x16x32_bf16 v[24:27], v[204:207], v[164:167], v[24:27]
	v_mfma_f32_16x16x32_bf16 v[28:31], v[240:243], v[164:167], v[28:31]
	v_mfma_f32_16x16x32_bf16 v[32:35], v[204:207], v[168:171], v[32:35]
	v_mfma_f32_16x16x32_bf16 v[36:39], v[240:243], v[168:171], v[36:39]
	v_mfma_f32_16x16x32_bf16 v[40:43], v[204:207], v[172:175], v[40:43]
	v_mfma_f32_16x16x32_bf16 v[44:47], v[240:243], v[172:175], v[44:47]
	v_mfma_f32_16x16x32_bf16 v[48:51], v[204:207], v[176:179], v[48:51]
	v_mfma_f32_16x16x32_bf16 v[52:55], v[240:243], v[176:179], v[52:55]
	ds_read_b128 v[164:167], v159 offset:24576
	ds_read_b128 v[168:171], v159 offset:26624
	ds_read_b128 v[172:175], v159 offset:28672
	ds_read_b128 v[176:179], v159 offset:30720
	ds_read_b128 v[180:183], v159 offset:32768
	s_waitcnt lgkmcnt(5)
	v_mfma_f32_16x16x32_bf16 v[56:59], v[204:207], v[136:139], v[56:59]
	v_mfma_f32_16x16x32_bf16 v[60:63], v[240:243], v[136:139], v[60:63]
	v_mfma_f32_16x16x32_bf16 v[64:67], v[204:207], v[140:143], v[64:67]
	v_mfma_f32_16x16x32_bf16 v[68:71], v[240:243], v[140:143], v[68:71]
	v_mfma_f32_16x16x32_bf16 v[72:75], v[204:207], v[144:147], v[72:75]
	v_mfma_f32_16x16x32_bf16 v[76:79], v[240:243], v[144:147], v[76:79]
	v_mfma_f32_16x16x32_bf16 v[80:83], v[204:207], v[148:151], v[80:83]
	v_mfma_f32_16x16x32_bf16 v[84:87], v[240:243], v[148:151], v[84:87]
	v_mfma_f32_16x16x32_bf16 v[88:91], v[204:207], v[152:155], v[88:91]
	v_mfma_f32_16x16x32_bf16 v[92:95], v[240:243], v[152:155], v[92:95]
	s_waitcnt vmcnt(0) lgkmcnt(0)
	s_barrier
	s_cmp_ge_u32 s63, 14
	s_cbranch_scc1 .Lg2_ff1_nd17_1
	ds_read_b128 v[136:139], v156 offset:0
	ds_read_b128 v[140:143], v156 offset:2048
	ds_read_b128 v[144:147], v156 offset:4096
	ds_read_b128 v[148:151], v156 offset:6144
	s_add_u32 s56, s56, 0x80
	s_addc_u32 s57, s57, 0
	s_add_u32 m0, s62, 0x8800
	s_add_u32 s4, s56, 0x0
	s_addc_u32 s5, s57, 0
	global_load_lds_dwordx4 v162, s[4:5]
	s_add_u32 m0, s62, 0x9800
	s_add_u32 s4, s56, 0x10000
	s_addc_u32 s5, s57, 0
	global_load_lds_dwordx4 v162, s[4:5]
	s_add_u32 m0, s62, 0xa800
	s_add_u32 s4, s56, 0x20000
	s_addc_u32 s5, s57, 0
	global_load_lds_dwordx4 v162, s[4:5]
	s_add_u32 m0, s62, 0xb800
	s_add_u32 s4, s56, 0x30000
	s_addc_u32 s5, s57, 0
	global_load_lds_dwordx4 v162, s[4:5]
	s_add_u32 m0, s62, 0xc800
	s_add_u32 s4, s56, 0x40000
	s_addc_u32 s5, s57, 0
	global_load_lds_dwordx4 v162, s[4:5]
	s_add_u32 m0, s62, 0xd800
	s_add_u32 s4, s56, 0x50000
	s_addc_u32 s5, s57, 0
	global_load_lds_dwordx4 v162, s[4:5]
	s_add_u32 m0, s62, 0xe800
	s_add_u32 s4, s56, 0x60000
	s_addc_u32 s5, s57, 0
	global_load_lds_dwordx4 v162, s[4:5]
	s_add_u32 m0, s62, 0xf800
	s_add_u32 s4, s56, 0x70000
	s_addc_u32 s5, s57, 0
	global_load_lds_dwordx4 v162, s[4:5]
	s_cmp_gt_u32 s70, 1
	s_cbranch_scc1 .Lg2_ff1_nodma_3
	s_add_u32 m0, s62, 0x10800
	s_add_u32 s4, s56, 0x80000
	s_addc_u32 s5, s57, 0
	global_load_lds_dwordx4 v162, s[4:5]

.Lg2_ff1_loop16:
	s_add_u32 s58, s58, 0x800
	s_addc_u32 s59, s59, 0
	global_load_dwordx4 v[200:203], v160, s[58:59] offset:0
	global_load_dwordx4 v[204:207], v160, s[58:59] offset:1024
	global_load_dwordx4 v[208:211], v161, s[58:59] offset:0
	global_load_dwordx4 v[240:243], v161, s[58:59] offset:1024
	ds_read_b128 v[164:167], v156 offset:8192
	ds_read_b128 v[168:171], v156 offset:10240
	ds_read_b128 v[172:175], v156 offset:12288
	ds_read_b128 v[176:179], v156 offset:14336
	s_waitcnt lgkmcnt(4)
	v_mfma_f32_16x16x32_bf16 v[0:3], v[184:187], v[136:139], v[0:3]
	v_mfma_f32_16x16x32_bf16 v[4:7], v[192:195], v[136:139], v[4:7]
	v_mfma_f32_16x16x32_bf16 v[8:11], v[184:187], v[140:143], v[8:11]
	v_mfma_f32_16x16x32_bf16 v[12:15], v[192:195], v[140:143], v[12:15]
	v_mfma_f32_16x16x32_bf16 v[16:19], v[184:187], v[144:147], v[16:19]
	v_mfma_f32_16x16x32_bf16 v[20:23], v[192:195], v[144:147], v[20:23]
	v_mfma_f32_16x16x32_bf16 v[24:27], v[184:187], v[148:151], v[24:27]
	v_mfma_f32_16x16x32_bf16 v[28:31], v[192:195], v[148:151], v[28:31]
	ds_read_b128 v[136:139], v156 offset:16384
	ds_read_b128 v[140:143], v156 offset:18432
	ds_read_b128 v[144:147], v156 offset:20480
	ds_read_b128 v[148:151], v156 offset:22528
	s_waitcnt lgkmcnt(4)
	v_mfma_f32_16x16x32_bf16 v[32:35], v[184:187], v[164:167], v[32:35]
	v_mfma_f32_16x16x32_bf16 v[36:39], v[192:195], v[164:167], v[36:39]
	v_mfma_f32_16x16x32_bf16 v[40:43], v[184:187], v[168:171], v[40:43]
	v_mfma_f32_16x16x32_bf16 v[44:47], v[192:195], v[168:171], v[44:47]
	v_mfma_f32_16x16x32_bf16 v[48:51], v[184:187], v[172:175], v[48:51]
	v_mfma_f32_16x16x32_bf16 v[52:55], v[192:195], v[172:175], v[52:55]
	v_mfma_f32_16x16x32_bf16 v[56:59], v[184:187], v[176:179], v[56:59]
	v_mfma_f32_16x16x32_bf16 v[60:63], v[192:195], v[176:179], v[60:63]
	ds_read_b128 v[164:167], v156 offset:24576
	ds_read_b128 v[168:171], v156 offset:26624
	ds_read_b128 v[172:175], v156 offset:28672
	ds_read_b128 v[176:179], v156 offset:30720
	s_waitcnt lgkmcnt(4)
	v_mfma_f32_16x16x32_bf16 v[64:67], v[184:187], v[136:139], v[64:67]
	v_mfma_f32_16x16x32_bf16 v[68:71], v[192:195], v[136:139], v[68:71]
	v_mfma_f32_16x16x32_bf16 v[72:75], v[184:187], v[140:143], v[72:75]
	v_mfma_f32_16x16x32_bf16 v[76:79], v[192:195], v[140:143], v[76:79]
	v_mfma_f32_16x16x32_bf16 v[80:83], v[184:187], v[144:147], v[80:83]
	v_mfma_f32_16x16x32_bf16 v[84:87], v[192:195], v[144:147], v[84:87]
	v_mfma_f32_16x16x32_bf16 v[88:91], v[184:187], v[148:151], v[88:91]
	v_mfma_f32_16x16x32_bf16 v[92:95], v[192:195], v[148:151], v[92:95]
	ds_read_b128 v[136:139], v157 offset:0
	ds_read_b128 v[140:143], v157 offset:2048
	ds_read_b128 v[144:147], v157 offset:4096
	s_waitcnt lgkmcnt(3)
	v_mfma_f32_16x16x32_bf16 v[96:99], v[184:187], v[164:167], v[96:99]
	v_mfma_f32_16x16x32_bf16 v[100:103], v[192:195], v[164:167], v[100:103]
	v_mfma_f32_16x16x32_bf16 v[104:107], v[184:187], v[168:171], v[104:107]
	v_mfma_f32_16x16x32_bf16 v[108:111], v[192:195], v[168:171], v[108:111]
	v_mfma_f32_16x16x32_bf16 v[112:115], v[184:187], v[172:175], v[112:115]
	v_mfma_f32_16x16x32_bf16 v[116:119], v[192:195], v[172:175], v[116:119]
	v_mfma_f32_16x16x32_bf16 v[120:123], v[184:187], v[176:179], v[120:123]
	v_mfma_f32_16x16x32_bf16 v[124:127], v[192:195], v[176:179], v[124:127]
	ds_read_b128 v[164:167], v157 offset:6144
	ds_read_b128 v[168:171], v157 offset:8192
	ds_read_b128 v[172:175], v157 offset:10240
	s_waitcnt lgkmcnt(3)
	v_mfma_f32_16x16x32_bf16 v[0:3], v[188:191], v[136:139], v[0:3]
	v_mfma_f32_16x16x32_bf16 v[4:7], v[196:199], v[136:139], v[4:7]
	v_mfma_f32_16x16x32_bf16 v[8:11], v[188:191], v[140:143], v[8:11]
	v_mfma_f32_16x16x32_bf16 v[12:15], v[196:199], v[140:143], v[12:15]
	v_mfma_f32_16x16x32_bf16 v[16:19], v[188:191], v[144:147], v[16:19]
	v_mfma_f32_16x16x32_bf16 v[20:23], v[196:199], v[144:147], v[20:23]
	ds_read_b128 v[136:139], v157 offset:12288
	ds_read_b128 v[140:143], v157 offset:14336
	ds_read_b128 v[144:147], v157 offset:16384
	ds_read_b128 v[148:151], v157 offset:18432
	ds_read_b128 v[152:155], v157 offset:20480
	s_waitcnt lgkmcnt(5)
	v_mfma_f32_16x16x32_bf16 v[24:27], v[188:191], v[164:167], v[24:27]
	v_mfma_f32_16x16x32_bf16 v[28:31], v[196:199], v[164:167], v[28:31]
	v_mfma_f32_16x16x32_bf16 v[32:35], v[188:191], v[168:171], v[32:35]
	v_mfma_f32_16x16x32_bf16 v[36:39], v[196:199], v[168:171], v[36:39]
	v_mfma_f32_16x16x32_bf16 v[40:43], v[188:191], v[172:175], v[40:43]
	v_mfma_f32_16x16x32_bf16 v[44:47], v[196:199], v[172:175], v[44:47]
	ds_read_b128 v[164:167], v157 offset:22528
	ds_read_b128 v[168:171], v157 offset:24576
	ds_read_b128 v[172:175], v157 offset:26624
	ds_read_b128 v[176:179], v157 offset:28672
	ds_read_b128 v[180:183], v157 offset:30720
	s_waitcnt lgkmcnt(5)
	v_mfma_f32_16x16x32_bf16 v[48:51], v[188:191], v[136:139], v[48:51]
	v_mfma_f32_16x16x32_bf16 v[52:55], v[196:199], v[136:139], v[52:55]
	v_mfma_f32_16x16x32_bf16 v[56:59], v[188:191], v[140:143], v[56:59]
	v_mfma_f32_16x16x32_bf16 v[60:63], v[196:199], v[140:143], v[60:63]
	v_mfma_f32_16x16x32_bf16 v[64:67], v[188:191], v[144:147], v[64:67]
	v_mfma_f32_16x16x32_bf16 v[68:71], v[196:199], v[144:147], v[68:71]
	v_mfma_f32_16x16x32_bf16 v[72:75], v[188:191], v[148:151], v[72:75]
	v_mfma_f32_16x16x32_bf16 v[76:79], v[196:199], v[148:151], v[76:79]
	v_mfma_f32_16x16x32_bf16 v[80:83], v[188:191], v[152:155], v[80:83]
	v_mfma_f32_16x16x32_bf16 v[84:87], v[196:199], v[152:155], v[84:87]
	s_waitcnt vmcnt(0) lgkmcnt(0)
	s_barrier
	ds_read_b128 v[136:139], v158 offset:0
	ds_read_b128 v[140:143], v158 offset:2048
	ds_read_b128 v[144:147], v158 offset:4096
	ds_read_b128 v[148:151], v158 offset:6144
	s_cmp_ge_u32 s63, 14
	s_cbranch_scc1 .Lg2_ff1_nd16_0
	s_add_u32 s56, s56, 0x80
	s_addc_u32 s57, s57, 0
	s_add_u32 m0, s62, 0x0
	s_add_u32 s4, s56, 0x0
	s_addc_u32 s5, s57, 0
	global_load_lds_dwordx4 v162, s[4:5]
	s_add_u32 m0, s62, 0x1000
	s_add_u32 s4, s56, 0x10000
	s_addc_u32 s5, s57, 0
	global_load_lds_dwordx4 v162, s[4:5]
	s_add_u32 m0, s62, 0x2000
	s_add_u32 s4, s56, 0x20000
	s_addc_u32 s5, s57, 0
	global_load_lds_dwordx4 v162, s[4:5]
	s_add_u32 m0, s62, 0x3000
	s_add_u32 s4, s56, 0x30000
	s_addc_u32 s5, s57, 0
	global_load_lds_dwordx4 v162, s[4:5]
	s_add_u32 m0, s62, 0x4000
	s_add_u32 s4, s56, 0x40000
	s_addc_u32 s5, s57, 0
	global_load_lds_dwordx4 v162, s[4:5]
	s_add_u32 m0, s62, 0x5000
	s_add_u32 s4, s56, 0x50000
	s_addc_u32 s5, s57, 0
	global_load_lds_dwordx4 v162, s[4:5]
	s_add_u32 m0, s62, 0x6000
	s_add_u32 s4, s56, 0x60000
	s_addc_u32 s5, s57, 0
	global_load_lds_dwordx4 v162, s[4:5]
	s_add_u32 m0, s62, 0x7000
	s_add_u32 s4, s56, 0x70000
	s_addc_u32 s5, s57, 0
	global_load_lds_dwordx4 v162, s[4:5]
.Lg2_ff1_nd16_0:
	v_mfma_f32_16x16x32_bf16 v[88:91], v[188:191], v[164:167], v[88:91]
	v_mfma_f32_16x16x32_bf16 v[92:95], v[196:199], v[164:167], v[92:95]
	v_mfma_f32_16x16x32_bf16 v[96:99], v[188:191], v[168:171], v[96:99]
	v_mfma_f32_16x16x32_bf16 v[100:103], v[196:199], v[168:171], v[100:103]
	v_mfma_f32_16x16x32_bf16 v[104:107], v[188:191], v[172:175], v[104:107]
	v_mfma_f32_16x16x32_bf16 v[108:111], v[196:199], v[172:175], v[108:111]
	v_mfma_f32_16x16x32_bf16 v[112:115], v[188:191], v[176:179], v[112:115]
	v_mfma_f32_16x16x32_bf16 v[116:119], v[196:199], v[176:179], v[116:119]
	v_mfma_f32_16x16x32_bf16 v[120:123], v[188:191], v[180:183], v[120:123]
	v_mfma_f32_16x16x32_bf16 v[124:127], v[196:199], v[180:183], v[124:127]
	s_cmp_ge_u32 s63, 14
	s_cbranch_scc1 .Lg2_ff1_nb16_1
	s_add_u32 s58, s58, 0x800
	s_addc_u32 s59, s59, 0
	global_load_dwordx4 v[184:187], v160, s[58:59] offset:0
	global_load_dwordx4 v[188:191], v160, s[58:59] offset:1024
	global_load_dwordx4 v[192:195], v161, s[58:59] offset:0
	global_load_dwordx4 v[196:199], v161, s[58:59] offset:1024
.Lg2_ff1_nb16_1:
	ds_read_b128 v[164:167], v158 offset:8192
	ds_read_b128 v[168:171], v158 offset:10240
	ds_read_b128 v[172:175], v158 offset:12288
	ds_read_b128 v[176:179], v158 offset:14336
	s_waitcnt lgkmcnt(4)
	v_mfma_f32_16x16x32_bf16 v[0:3], v[200:203], v[136:139], v[0:3]
	v_mfma_f32_16x16x32_bf16 v[4:7], v[208:211], v[136:139], v[4:7]
	v_mfma_f32_16x16x32_bf16 v[8:11], v[200:203], v[140:143], v[8:11]
	v_mfma_f32_16x16x32_bf16 v[12:15], v[208:211], v[140:143], v[12:15]
	v_mfma_f32_16x16x32_bf16 v[16:19], v[200:203], v[144:147], v[16:19]
	v_mfma_f32_16x16x32_bf16 v[20:23], v[208:211], v[144:147], v[20:23]
	v_mfma_f32_16x16x32_bf16 v[24:27], v[200:203], v[148:151], v[24:27]
	v_mfma_f32_16x16x32_bf16 v[28:31], v[208:211], v[148:151], v[28:31]
	ds_read_b128 v[136:139], v158 offset:16384
	ds_read_b128 v[140:143], v158 offset:18432
	ds_read_b128 v[144:147], v158 offset:20480
	ds_read_b128 v[148:151], v158 offset:22528
	s_waitcnt lgkmcnt(4)
	v_mfma_f32_16x16x32_bf16 v[32:35], v[200:203], v[164:167], v[32:35]
	v_mfma_f32_16x16x32_bf16 v[36:39], v[208:211], v[164:167], v[36:39]
	v_mfma_f32_16x16x32_bf16 v[40:43], v[200:203], v[168:171], v[40:43]
	v_mfma_f32_16x16x32_bf16 v[44:47], v[208:211], v[168:171], v[44:47]
	v_mfma_f32_16x16x32_bf16 v[48:51], v[200:203], v[172:175], v[48:51]
	v_mfma_f32_16x16x32_bf16 v[52:55], v[208:211], v[172:175], v[52:55]
	v_mfma_f32_16x16x32_bf16 v[56:59], v[200:203], v[176:179], v[56:59]
	v_mfma_f32_16x16x32_bf16 v[60:63], v[208:211], v[176:179], v[60:63]
	ds_read_b128 v[164:167], v158 offset:24576
	ds_read_b128 v[168:171], v158 offset:26624
	ds_read_b128 v[172:175], v158 offset:28672
	ds_read_b128 v[176:179], v158 offset:30720
	s_waitcnt lgkmcnt(4)
	v_mfma_f32_16x16x32_bf16 v[64:67], v[200:203], v[136:139], v[64:67]
	v_mfma_f32_16x16x32_bf16 v[68:71], v[208:211], v[136:139], v[68:71]
	v_mfma_f32_16x16x32_bf16 v[72:75], v[200:203], v[140:143], v[72:75]
	v_mfma_f32_16x16x32_bf16 v[76:79], v[208:211], v[140:143], v[76:79]
	v_mfma_f32_16x16x32_bf16 v[80:83], v[200:203], v[144:147], v[80:83]
	v_mfma_f32_16x16x32_bf16 v[84:87], v[208:211], v[144:147], v[84:87]
	v_mfma_f32_16x16x32_bf16 v[88:91], v[200:203], v[148:151], v[88:91]
	v_mfma_f32_16x16x32_bf16 v[92:95], v[208:211], v[148:151], v[92:95]
	ds_read_b128 v[136:139], v159 offset:0
	ds_read_b128 v[140:143], v159 offset:2048
	ds_read_b128 v[144:147], v159 offset:4096
	s_waitcnt lgkmcnt(3)
	v_mfma_f32_16x16x32_bf16 v[96:99], v[200:203], v[164:167], v[96:99]
	v_mfma_f32_16x16x32_bf16 v[100:103], v[208:211], v[164:167], v[100:103]
	v_mfma_f32_16x16x32_bf16 v[104:107], v[200:203], v[168:171], v[104:107]
	v_mfma_f32_16x16x32_bf16 v[108:111], v[208:211], v[168:171], v[108:111]
	v_mfma_f32_16x16x32_bf16 v[112:115], v[200:203], v[172:175], v[112:115]
	v_mfma_f32_16x16x32_bf16 v[116:119], v[208:211], v[172:175], v[116:119]
	v_mfma_f32_16x16x32_bf16 v[120:123], v[200:203], v[176:179], v[120:123]
	v_mfma_f32_16x16x32_bf16 v[124:127], v[208:211], v[176:179], v[124:127]
	ds_read_b128 v[164:167], v159 offset:6144
	ds_read_b128 v[168:171], v159 offset:8192
	ds_read_b128 v[172:175], v159 offset:10240
	s_waitcnt lgkmcnt(3)
	v_mfma_f32_16x16x32_bf16 v[0:3], v[204:207], v[136:139], v[0:3]
	v_mfma_f32_16x16x32_bf16 v[4:7], v[240:243], v[136:139], v[4:7]
	v_mfma_f32_16x16x32_bf16 v[8:11], v[204:207], v[140:143], v[8:11]
	v_mfma_f32_16x16x32_bf16 v[12:15], v[240:243], v[140:143], v[12:15]
	v_mfma_f32_16x16x32_bf16 v[16:19], v[204:207], v[144:147], v[16:19]
	v_mfma_f32_16x16x32_bf16 v[20:23], v[240:243], v[144:147], v[20:23]
	ds_read_b128 v[136:139], v159 offset:12288
	ds_read_b128 v[140:143], v159 offset:14336
	ds_read_b128 v[144:147], v159 offset:16384
	ds_read_b128 v[148:151], v159 offset:18432
	ds_read_b128 v[152:155], v159 offset:20480
	s_waitcnt lgkmcnt(5)
	v_mfma_f32_16x16x32_bf16 v[24:27], v[204:207], v[164:167], v[24:27]
	v_mfma_f32_16x16x32_bf16 v[28:31], v[240:243], v[164:167], v[28:31]
	v_mfma_f32_16x16x32_bf16 v[32:35], v[204:207], v[168:171], v[32:35]
	v_mfma_f32_16x16x32_bf16 v[36:39], v[240:243], v[168:171], v[36:39]
	v_mfma_f32_16x16x32_bf16 v[40:43], v[204:207], v[172:175], v[40:43]
	v_mfma_f32_16x16x32_bf16 v[44:47], v[240:243], v[172:175], v[44:47]
	ds_read_b128 v[164:167], v159 offset:22528
	ds_read_b128 v[168:171], v159 offset:24576
	ds_read_b128 v[172:175], v159 offset:26624
	ds_read_b128 v[176:179], v159 offset:28672
	ds_read_b128 v[180:183], v159 offset:30720
	s_waitcnt lgkmcnt(5)
	v_mfma_f32_16x16x32_bf16 v[48:51], v[204:207], v[136:139], v[48:51]
	v_mfma_f32_16x16x32_bf16 v[52:55], v[240:243], v[136:139], v[52:55]
	v_mfma_f32_16x16x32_bf16 v[56:59], v[204:207], v[140:143], v[56:59]
	v_mfma_f32_16x16x32_bf16 v[60:63], v[240:243], v[140:143], v[60:63]
	v_mfma_f32_16x16x32_bf16 v[64:67], v[204:207], v[144:147], v[64:67]
	v_mfma_f32_16x16x32_bf16 v[68:71], v[240:243], v[144:147], v[68:71]
	v_mfma_f32_16x16x32_bf16 v[72:75], v[204:207], v[148:151], v[72:75]
	v_mfma_f32_16x16x32_bf16 v[76:79], v[240:243], v[148:151], v[76:79]
	v_mfma_f32_16x16x32_bf16 v[80:83], v[204:207], v[152:155], v[80:83]
	v_mfma_f32_16x16x32_bf16 v[84:87], v[240:243], v[152:155], v[84:87]
	s_waitcnt vmcnt(0) lgkmcnt(0)
	s_barrier
	s_cmp_ge_u32 s63, 14
	s_cbranch_scc1 .Lg2_ff1_nd16_1
	ds_read_b128 v[136:139], v156 offset:0
	ds_read_b128 v[140:143], v156 offset:2048
	ds_read_b128 v[144:147], v156 offset:4096
	ds_read_b128 v[148:151], v156 offset:6144
	s_add_u32 s56, s56, 0x80
	s_addc_u32 s57, s57, 0
	s_add_u32 m0, s62, 0x8800
	s_add_u32 s4, s56, 0x0
	s_addc_u32 s5, s57, 0
	global_load_lds_dwordx4 v162, s[4:5]
	s_add_u32 m0, s62, 0x9800
	s_add_u32 s4, s56, 0x10000
	s_addc_u32 s5, s57, 0
	global_load_lds_dwordx4 v162, s[4:5]
	s_add_u32 m0, s62, 0xa800
	s_add_u32 s4, s56, 0x20000
	s_addc_u32 s5, s57, 0
	global_load_lds_dwordx4 v162, s[4:5]
	s_add_u32 m0, s62, 0xb800
	s_add_u32 s4, s56, 0x30000
	s_addc_u32 s5, s57, 0
	global_load_lds_dwordx4 v162, s[4:5]
	s_add_u32 m0, s62, 0xc800
	s_add_u32 s4, s56, 0x40000
	s_addc_u32 s5, s57, 0
	global_load_lds_dwordx4 v162, s[4:5]
	s_add_u32 m0, s62, 0xd800
	s_add_u32 s4, s56, 0x50000
	s_addc_u32 s5, s57, 0
	global_load_lds_dwordx4 v162, s[4:5]
	s_add_u32 m0, s62, 0xe800
	s_add_u32 s4, s56, 0x60000
	s_addc_u32 s5, s57, 0
	global_load_lds_dwordx4 v162, s[4:5]
	s_add_u32 m0, s62, 0xf800
	s_add_u32 s4, s56, 0x70000
	s_addc_u32 s5, s57, 0
	global_load_lds_dwordx4 v162, s[4:5]

.Lg2_up_loop17:
	s_add_u32 s58, s58, 0x800
	s_addc_u32 s59, s59, 0
	global_load_dwordx4 v[200:203], v160, s[58:59] offset:0
	global_load_dwordx4 v[204:207], v160, s[58:59] offset:1024
	global_load_dwordx4 v[208:211], v161, s[58:59] offset:0
	global_load_dwordx4 v[240:243], v161, s[58:59] offset:1024
	ds_read_b128 v[164:167], v156 offset:8192
	ds_read_b128 v[168:171], v156 offset:10240
	ds_read_b128 v[172:175], v156 offset:12288
	ds_read_b128 v[176:179], v156 offset:14336
	s_waitcnt lgkmcnt(4)
	v_mfma_f32_16x16x32_bf16 v[0:3], v[184:187], v[136:139], v[0:3]
	v_mfma_f32_16x16x32_bf16 v[4:7], v[192:195], v[136:139], v[4:7]
	v_mfma_f32_16x16x32_bf16 v[8:11], v[184:187], v[140:143], v[8:11]
	v_mfma_f32_16x16x32_bf16 v[12:15], v[192:195], v[140:143], v[12:15]
	v_mfma_f32_16x16x32_bf16 v[16:19], v[184:187], v[144:147], v[16:19]
	v_mfma_f32_16x16x32_bf16 v[20:23], v[192:195], v[144:147], v[20:23]
	v_mfma_f32_16x16x32_bf16 v[24:27], v[184:187], v[148:151], v[24:27]
	v_mfma_f32_16x16x32_bf16 v[28:31], v[192:195], v[148:151], v[28:31]
	ds_read_b128 v[136:139], v156 offset:16384
	ds_read_b128 v[140:143], v156 offset:18432
	ds_read_b128 v[144:147], v156 offset:20480
	ds_read_b128 v[148:151], v156 offset:22528
	s_waitcnt lgkmcnt(4)
	v_mfma_f32_16x16x32_bf16 v[32:35], v[184:187], v[164:167], v[32:35]
	v_mfma_f32_16x16x32_bf16 v[36:39], v[192:195], v[164:167], v[36:39]
	v_mfma_f32_16x16x32_bf16 v[40:43], v[184:187], v[168:171], v[40:43]
	v_mfma_f32_16x16x32_bf16 v[44:47], v[192:195], v[168:171], v[44:47]
	v_mfma_f32_16x16x32_bf16 v[48:51], v[184:187], v[172:175], v[48:51]
	v_mfma_f32_16x16x32_bf16 v[52:55], v[192:195], v[172:175], v[52:55]
	v_mfma_f32_16x16x32_bf16 v[56:59], v[184:187], v[176:179], v[56:59]
	v_mfma_f32_16x16x32_bf16 v[60:63], v[192:195], v[176:179], v[60:63]
	ds_read_b128 v[164:167], v156 offset:24576
	ds_read_b128 v[168:171], v156 offset:26624
	ds_read_b128 v[172:175], v156 offset:28672
	ds_read_b128 v[176:179], v156 offset:30720
	ds_read_b128 v[180:183], v156 offset:32768
	s_waitcnt lgkmcnt(5)
	v_mfma_f32_16x16x32_bf16 v[64:67], v[184:187], v[136:139], v[64:67]
	v_mfma_f32_16x16x32_bf16 v[68:71], v[192:195], v[136:139], v[68:71]
	v_mfma_f32_16x16x32_bf16 v[72:75], v[184:187], v[140:143], v[72:75]
	v_mfma_f32_16x16x32_bf16 v[76:79], v[192:195], v[140:143], v[76:79]
	v_mfma_f32_16x16x32_bf16 v[80:83], v[184:187], v[144:147], v[80:83]
	v_mfma_f32_16x16x32_bf16 v[84:87], v[192:195], v[144:147], v[84:87]
	v_mfma_f32_16x16x32_bf16 v[88:91], v[184:187], v[148:151], v[88:91]
	v_mfma_f32_16x16x32_bf16 v[92:95], v[192:195], v[148:151], v[92:95]
	ds_read_b128 v[136:139], v157 offset:0
	ds_read_b128 v[140:143], v157 offset:2048
	ds_read_b128 v[144:147], v157 offset:4096
	s_waitcnt lgkmcnt(3)
	v_mfma_f32_16x16x32_bf16 v[96:99], v[184:187], v[164:167], v[96:99]
	v_mfma_f32_16x16x32_bf16 v[100:103], v[192:195], v[164:167], v[100:103]
	v_mfma_f32_16x16x32_bf16 v[104:107], v[184:187], v[168:171], v[104:107]
	v_mfma_f32_16x16x32_bf16 v[108:111], v[192:195], v[168:171], v[108:111]
	v_mfma_f32_16x16x32_bf16 v[112:115], v[184:187], v[172:175], v[112:115]
	v_mfma_f32_16x16x32_bf16 v[116:119], v[192:195], v[172:175], v[116:119]
	v_mfma_f32_16x16x32_bf16 v[120:123], v[184:187], v[176:179], v[120:123]
	v_mfma_f32_16x16x32_bf16 v[124:127], v[192:195], v[176:179], v[124:127]
	v_mfma_f32_16x16x32_bf16 v[128:131], v[184:187], v[180:183], v[128:131]
	v_mfma_f32_16x16x32_bf16 v[132:135], v[192:195], v[180:183], v[132:135]
	ds_read_b128 v[164:167], v157 offset:6144
	ds_read_b128 v[168:171], v157 offset:8192
	ds_read_b128 v[172:175], v157 offset:10240
	ds_read_b128 v[176:179], v157 offset:12288
	s_waitcnt lgkmcnt(4)
	v_mfma_f32_16x16x32_bf16 v[0:3], v[188:191], v[136:139], v[0:3]
	v_mfma_f32_16x16x32_bf16 v[4:7], v[196:199], v[136:139], v[4:7]
	v_mfma_f32_16x16x32_bf16 v[8:11], v[188:191], v[140:143], v[8:11]
	v_mfma_f32_16x16x32_bf16 v[12:15], v[196:199], v[140:143], v[12:15]
	v_mfma_f32_16x16x32_bf16 v[16:19], v[188:191], v[144:147], v[16:19]
	v_mfma_f32_16x16x32_bf16 v[20:23], v[196:199], v[144:147], v[20:23]
	ds_read_b128 v[136:139], v157 offset:14336
	ds_read_b128 v[140:143], v157 offset:16384
	ds_read_b128 v[144:147], v157 offset:18432
	ds_read_b128 v[148:151], v157 offset:20480
	ds_read_b128 v[152:155], v157 offset:22528
	s_waitcnt lgkmcnt(5)
	v_mfma_f32_16x16x32_bf16 v[24:27], v[188:191], v[164:167], v[24:27]
	v_mfma_f32_16x16x32_bf16 v[28:31], v[196:199], v[164:167], v[28:31]
	v_mfma_f32_16x16x32_bf16 v[32:35], v[188:191], v[168:171], v[32:35]
	v_mfma_f32_16x16x32_bf16 v[36:39], v[196:199], v[168:171], v[36:39]
	v_mfma_f32_16x16x32_bf16 v[40:43], v[188:191], v[172:175], v[40:43]
	v_mfma_f32_16x16x32_bf16 v[44:47], v[196:199], v[172:175], v[44:47]
	v_mfma_f32_16x16x32_bf16 v[48:51], v[188:191], v[176:179], v[48:51]
	v_mfma_f32_16x16x32_bf16 v[52:55], v[196:199], v[176:179], v[52:55]
	ds_read_b128 v[164:167], v157 offset:24576
	ds_read_b128 v[168:171], v157 offset:26624
	ds_read_b128 v[172:175], v157 offset:28672
	ds_read_b128 v[176:179], v157 offset:30720
	ds_read_b128 v[180:183], v157 offset:32768
	s_waitcnt lgkmcnt(5)
	v_mfma_f32_16x16x32_bf16 v[56:59], v[188:191], v[136:139], v[56:59]
	v_mfma_f32_16x16x32_bf16 v[60:63], v[196:199], v[136:139], v[60:63]
	v_mfma_f32_16x16x32_bf16 v[64:67], v[188:191], v[140:143], v[64:67]
	v_mfma_f32_16x16x32_bf16 v[68:71], v[196:199], v[140:143], v[68:71]
	v_mfma_f32_16x16x32_bf16 v[72:75], v[188:191], v[144:147], v[72:75]
	v_mfma_f32_16x16x32_bf16 v[76:79], v[196:199], v[144:147], v[76:79]
	v_mfma_f32_16x16x32_bf16 v[80:83], v[188:191], v[148:151], v[80:83]
	v_mfma_f32_16x16x32_bf16 v[84:87], v[196:199], v[148:151], v[84:87]
	v_mfma_f32_16x16x32_bf16 v[88:91], v[188:191], v[152:155], v[88:91]
	v_mfma_f32_16x16x32_bf16 v[92:95], v[196:199], v[152:155], v[92:95]
	s_waitcnt vmcnt(0) lgkmcnt(0)
	s_barrier
	ds_read_b128 v[136:139], v158 offset:0
	ds_read_b128 v[140:143], v158 offset:2048
	ds_read_b128 v[144:147], v158 offset:4096
	ds_read_b128 v[148:151], v158 offset:6144
	s_cmp_ge_u32 s63, 2
	s_cbranch_scc1 .Lg2_up_nd17_0
	s_add_u32 s56, s56, 0x80
	s_addc_u32 s57, s57, 0
	s_add_u32 m0, s62, 0x0
	s_add_u32 s4, s56, 0x0
	s_addc_u32 s5, s57, 0
	global_load_lds_dwordx4 v162, s[4:5]
	s_add_u32 m0, s62, 0x1000
	s_add_u32 s4, s56, 0x72000
	s_addc_u32 s5, s57, 0
	global_load_lds_dwordx4 v162, s[4:5]
	s_add_u32 m0, s62, 0x2000
	s_add_u32 s4, s56, 0xe4000
	s_addc_u32 s5, s57, 0
	global_load_lds_dwordx4 v162, s[4:5]
	s_add_u32 m0, s62, 0x3000
	s_add_u32 s4, s56, 0x156000
	s_addc_u32 s5, s57, 0
	global_load_lds_dwordx4 v162, s[4:5]
	s_add_u32 m0, s62, 0x4000
	s_add_u32 s4, s56, 0x1c8000
	s_addc_u32 s5, s57, 0
	global_load_lds_dwordx4 v162, s[4:5]
	s_add_u32 m0, s62, 0x5000
	s_add_u32 s4, s56, 0x23a000
	s_addc_u32 s5, s57, 0
	global_load_lds_dwordx4 v162, s[4:5]
	s_add_u32 m0, s62, 0x6000
	s_add_u32 s4, s56, 0x2ac000
	s_addc_u32 s5, s57, 0
	global_load_lds_dwordx4 v162, s[4:5]
	s_add_u32 m0, s62, 0x7000
	s_add_u32 s4, s56, 0x31e000
	s_addc_u32 s5, s57, 0
	global_load_lds_dwordx4 v162, s[4:5]
	s_cmp_gt_u32 s70, 1
	s_cbranch_scc1 .Lg2_up_nodma_2
	s_add_u32 m0, s62, 0x8000
	s_add_u32 s4, s56, 0x390000
	s_addc_u32 s5, s57, 0
	global_load_lds_dwordx4 v162, s[4:5]

.Lg2_up_nb17_1:
	ds_read_b128 v[164:167], v158 offset:8192
	ds_read_b128 v[168:171], v158 offset:10240
	ds_read_b128 v[172:175], v158 offset:12288
	ds_read_b128 v[176:179], v158 offset:14336
	s_waitcnt lgkmcnt(4)
	v_mfma_f32_16x16x32_bf16 v[0:3], v[200:203], v[136:139], v[0:3]
	v_mfma_f32_16x16x32_bf16 v[4:7], v[208:211], v[136:139], v[4:7]
	v_mfma_f32_16x16x32_bf16 v[8:11], v[200:203], v[140:143], v[8:11]
	v_mfma_f32_16x16x32_bf16 v[12:15], v[208:211], v[140:143], v[12:15]
	v_mfma_f32_16x16x32_bf16 v[16:19], v[200:203], v[144:147], v[16:19]
	v_mfma_f32_16x16x32_bf16 v[20:23], v[208:211], v[144:147], v[20:23]
	v_mfma_f32_16x16x32_bf16 v[24:27], v[200:203], v[148:151], v[24:27]
	v_mfma_f32_16x16x32_bf16 v[28:31], v[208:211], v[148:151], v[28:31]
	ds_read_b128 v[136:139], v158 offset:16384
	ds_read_b128 v[140:143], v158 offset:18432
	ds_read_b128 v[144:147], v158 offset:20480
	ds_read_b128 v[148:151], v158 offset:22528
	s_waitcnt lgkmcnt(4)
	v_mfma_f32_16x16x32_bf16 v[32:35], v[200:203], v[164:167], v[32:35]
	v_mfma_f32_16x16x32_bf16 v[36:39], v[208:211], v[164:167], v[36:39]
	v_mfma_f32_16x16x32_bf16 v[40:43], v[200:203], v[168:171], v[40:43]
	v_mfma_f32_16x16x32_bf16 v[44:47], v[208:211], v[168:171], v[44:47]
	v_mfma_f32_16x16x32_bf16 v[48:51], v[200:203], v[172:175], v[48:51]
	v_mfma_f32_16x16x32_bf16 v[52:55], v[208:211], v[172:175], v[52:55]
	v_mfma_f32_16x16x32_bf16 v[56:59], v[200:203], v[176:179], v[56:59]
	v_mfma_f32_16x16x32_bf16 v[60:63], v[208:211], v[176:179], v[60:63]
	ds_read_b128 v[164:167], v158 offset:24576
	ds_read_b128 v[168:171], v158 offset:26624
	ds_read_b128 v[172:175], v158 offset:28672
	ds_read_b128 v[176:179], v158 offset:30720
	ds_read_b128 v[180:183], v158 offset:32768
	s_waitcnt lgkmcnt(5)
	v_mfma_f32_16x16x32_bf16 v[64:67], v[200:203], v[136:139], v[64:67]
	v_mfma_f32_16x16x32_bf16 v[68:71], v[208:211], v[136:139], v[68:71]
	v_mfma_f32_16x16x32_bf16 v[72:75], v[200:203], v[140:143], v[72:75]
	v_mfma_f32_16x16x32_bf16 v[76:79], v[208:211], v[140:143], v[76:79]
	v_mfma_f32_16x16x32_bf16 v[80:83], v[200:203], v[144:147], v[80:83]
	v_mfma_f32_16x16x32_bf16 v[84:87], v[208:211], v[144:147], v[84:87]
	v_mfma_f32_16x16x32_bf16 v[88:91], v[200:203], v[148:151], v[88:91]
	v_mfma_f32_16x16x32_bf16 v[92:95], v[208:211], v[148:151], v[92:95]
	ds_read_b128 v[136:139], v159 offset:0
	ds_read_b128 v[140:143], v159 offset:2048
	ds_read_b128 v[144:147], v159 offset:4096
	s_waitcnt lgkmcnt(3)
	v_mfma_f32_16x16x32_bf16 v[96:99], v[200:203], v[164:167], v[96:99]
	v_mfma_f32_16x16x32_bf16 v[100:103], v[208:211], v[164:167], v[100:103]
	v_mfma_f32_16x16x32_bf16 v[104:107], v[200:203], v[168:171], v[104:107]
	v_mfma_f32_16x16x32_bf16 v[108:111], v[208:211], v[168:171], v[108:111]
	v_mfma_f32_16x16x32_bf16 v[112:115], v[200:203], v[172:175], v[112:115]
	v_mfma_f32_16x16x32_bf16 v[116:119], v[208:211], v[172:175], v[116:119]
	v_mfma_f32_16x16x32_bf16 v[120:123], v[200:203], v[176:179], v[120:123]
	v_mfma_f32_16x16x32_bf16 v[124:127], v[208:211], v[176:179], v[124:127]
	v_mfma_f32_16x16x32_bf16 v[128:131], v[200:203], v[180:183], v[128:131]
	v_mfma_f32_16x16x32_bf16 v[132:135], v[208:211], v[180:183], v[132:135]
	ds_read_b128 v[164:167], v159 offset:6144
	ds_read_b128 v[168:171], v159 offset:8192
	ds_read_b128 v[172:175], v159 offset:10240
	ds_read_b128 v[176:179], v159 offset:12288
	s_waitcnt lgkmcnt(4)
	v_mfma_f32_16x16x32_bf16 v[0:3], v[204:207], v[136:139], v[0:3]
	v_mfma_f32_16x16x32_bf16 v[4:7], v[240:243], v[136:139], v[4:7]
	v_mfma_f32_16x16x32_bf16 v[8:11], v[204:207], v[140:143], v[8:11]
	v_mfma_f32_16x16x32_bf16 v[12:15], v[240:243], v[140:143], v[12:15]
	v_mfma_f32_16x16x32_bf16 v[16:19], v[204:207], v[144:147], v[16:19]
	v_mfma_f32_16x16x32_bf16 v[20:23], v[240:243], v[144:147], v[20:23]
	ds_read_b128 v[136:139], v159 offset:14336
	ds_read_b128 v[140:143], v159 offset:16384
	ds_read_b128 v[144:147], v159 offset:18432
	ds_read_b128 v[148:151], v159 offset:20480
	ds_read_b128 v[152:155], v159 offset:22528
	s_waitcnt lgkmcnt(5)
	v_mfma_f32_16x16x32_bf16 v[24:27], v[204:207], v[164:167], v[24:27]
	v_mfma_f32_16x16x32_bf16 v[28:31], v[240:243], v[164:167], v[28:31]
	v_mfma_f32_16x16x32_bf16 v[32:35], v[204:207], v[168:171], v[32:35]
	v_mfma_f32_16x16x32_bf16 v[36:39], v[240:243], v[168:171], v[36:39]
	v_mfma_f32_16x16x32_bf16 v[40:43], v[204:207], v[172:175], v[40:43]
	v_mfma_f32_16x16x32_bf16 v[44:47], v[240:243], v[172:175], v[44:47]
	v_mfma_f32_16x16x32_bf16 v[48:51], v[204:207], v[176:179], v[48:51]
	v_mfma_f32_16x16x32_bf16 v[52:55], v[240:243], v[176:179], v[52:55]
	ds_read_b128 v[164:167], v159 offset:24576
	ds_read_b128 v[168:171], v159 offset:26624
	ds_read_b128 v[172:175], v159 offset:28672
	ds_read_b128 v[176:179], v159 offset:30720
	ds_read_b128 v[180:183], v159 offset:32768
	s_waitcnt lgkmcnt(5)
	v_mfma_f32_16x16x32_bf16 v[56:59], v[204:207], v[136:139], v[56:59]
	v_mfma_f32_16x16x32_bf16 v[60:63], v[240:243], v[136:139], v[60:63]
	v_mfma_f32_16x16x32_bf16 v[64:67], v[204:207], v[140:143], v[64:67]
	v_mfma_f32_16x16x32_bf16 v[68:71], v[240:243], v[140:143], v[68:71]
	v_mfma_f32_16x16x32_bf16 v[72:75], v[204:207], v[144:147], v[72:75]
	v_mfma_f32_16x16x32_bf16 v[76:79], v[240:243], v[144:147], v[76:79]
	v_mfma_f32_16x16x32_bf16 v[80:83], v[204:207], v[148:151], v[80:83]
	v_mfma_f32_16x16x32_bf16 v[84:87], v[240:243], v[148:151], v[84:87]
	v_mfma_f32_16x16x32_bf16 v[88:91], v[204:207], v[152:155], v[88:91]
	v_mfma_f32_16x16x32_bf16 v[92:95], v[240:243], v[152:155], v[92:95]
	s_waitcnt vmcnt(0) lgkmcnt(0)
	s_barrier
	s_cmp_ge_u32 s63, 2
	s_cbranch_scc1 .Lg2_up_nd17_1
	ds_read_b128 v[136:139], v156 offset:0
	ds_read_b128 v[140:143], v156 offset:2048
	ds_read_b128 v[144:147], v156 offset:4096
	ds_read_b128 v[148:151], v156 offset:6144
	s_add_u32 s56, s56, 0x80
	s_addc_u32 s57, s57, 0
	s_add_u32 m0, s62, 0x8800
	s_add_u32 s4, s56, 0x0
	s_addc_u32 s5, s57, 0
	global_load_lds_dwordx4 v162, s[4:5]
	s_add_u32 m0, s62, 0x9800
	s_add_u32 s4, s56, 0x72000
	s_addc_u32 s5, s57, 0
	global_load_lds_dwordx4 v162, s[4:5]
	s_add_u32 m0, s62, 0xa800
	s_add_u32 s4, s56, 0xe4000
	s_addc_u32 s5, s57, 0
	global_load_lds_dwordx4 v162, s[4:5]
	s_add_u32 m0, s62, 0xb800
	s_add_u32 s4, s56, 0x156000
	s_addc_u32 s5, s57, 0
	global_load_lds_dwordx4 v162, s[4:5]
	s_add_u32 m0, s62, 0xc800
	s_add_u32 s4, s56, 0x1c8000
	s_addc_u32 s5, s57, 0
	global_load_lds_dwordx4 v162, s[4:5]
	s_add_u32 m0, s62, 0xd800
	s_add_u32 s4, s56, 0x23a000
	s_addc_u32 s5, s57, 0
	global_load_lds_dwordx4 v162, s[4:5]
	s_add_u32 m0, s62, 0xe800
	s_add_u32 s4, s56, 0x2ac000
	s_addc_u32 s5, s57, 0
	global_load_lds_dwordx4 v162, s[4:5]
	s_add_u32 m0, s62, 0xf800
	s_add_u32 s4, s56, 0x31e000
	s_addc_u32 s5, s57, 0
	global_load_lds_dwordx4 v162, s[4:5]
	s_cmp_gt_u32 s70, 1
	s_cbranch_scc1 .Lg2_up_nodma_3
	s_add_u32 m0, s62, 0x10800
	s_add_u32 s4, s56, 0x390000
	s_addc_u32 s5, s57, 0
	global_load_lds_dwordx4 v162, s[4:5]

.Lg2_up_loop16:
	s_add_u32 s58, s58, 0x800
	s_addc_u32 s59, s59, 0
	global_load_dwordx4 v[200:203], v160, s[58:59] offset:0
	global_load_dwordx4 v[204:207], v160, s[58:59] offset:1024
	global_load_dwordx4 v[208:211], v161, s[58:59] offset:0
	global_load_dwordx4 v[240:243], v161, s[58:59] offset:1024
	ds_read_b128 v[164:167], v156 offset:8192
	ds_read_b128 v[168:171], v156 offset:10240
	ds_read_b128 v[172:175], v156 offset:12288
	ds_read_b128 v[176:179], v156 offset:14336
	s_waitcnt lgkmcnt(4)
	v_mfma_f32_16x16x32_bf16 v[0:3], v[184:187], v[136:139], v[0:3]
	v_mfma_f32_16x16x32_bf16 v[4:7], v[192:195], v[136:139], v[4:7]
	v_mfma_f32_16x16x32_bf16 v[8:11], v[184:187], v[140:143], v[8:11]
	v_mfma_f32_16x16x32_bf16 v[12:15], v[192:195], v[140:143], v[12:15]
	v_mfma_f32_16x16x32_bf16 v[16:19], v[184:187], v[144:147], v[16:19]
	v_mfma_f32_16x16x32_bf16 v[20:23], v[192:195], v[144:147], v[20:23]
	v_mfma_f32_16x16x32_bf16 v[24:27], v[184:187], v[148:151], v[24:27]
	v_mfma_f32_16x16x32_bf16 v[28:31], v[192:195], v[148:151], v[28:31]
	ds_read_b128 v[136:139], v156 offset:16384
	ds_read_b128 v[140:143], v156 offset:18432
	ds_read_b128 v[144:147], v156 offset:20480
	ds_read_b128 v[148:151], v156 offset:22528
	s_waitcnt lgkmcnt(4)
	v_mfma_f32_16x16x32_bf16 v[32:35], v[184:187], v[164:167], v[32:35]
	v_mfma_f32_16x16x32_bf16 v[36:39], v[192:195], v[164:167], v[36:39]
	v_mfma_f32_16x16x32_bf16 v[40:43], v[184:187], v[168:171], v[40:43]
	v_mfma_f32_16x16x32_bf16 v[44:47], v[192:195], v[168:171], v[44:47]
	v_mfma_f32_16x16x32_bf16 v[48:51], v[184:187], v[172:175], v[48:51]
	v_mfma_f32_16x16x32_bf16 v[52:55], v[192:195], v[172:175], v[52:55]
	v_mfma_f32_16x16x32_bf16 v[56:59], v[184:187], v[176:179], v[56:59]
	v_mfma_f32_16x16x32_bf16 v[60:63], v[192:195], v[176:179], v[60:63]
	ds_read_b128 v[164:167], v156 offset:24576
	ds_read_b128 v[168:171], v156 offset:26624
	ds_read_b128 v[172:175], v156 offset:28672
	ds_read_b128 v[176:179], v156 offset:30720
	s_waitcnt lgkmcnt(4)
	v_mfma_f32_16x16x32_bf16 v[64:67], v[184:187], v[136:139], v[64:67]
	v_mfma_f32_16x16x32_bf16 v[68:71], v[192:195], v[136:139], v[68:71]
	v_mfma_f32_16x16x32_bf16 v[72:75], v[184:187], v[140:143], v[72:75]
	v_mfma_f32_16x16x32_bf16 v[76:79], v[192:195], v[140:143], v[76:79]
	v_mfma_f32_16x16x32_bf16 v[80:83], v[184:187], v[144:147], v[80:83]
	v_mfma_f32_16x16x32_bf16 v[84:87], v[192:195], v[144:147], v[84:87]
	v_mfma_f32_16x16x32_bf16 v[88:91], v[184:187], v[148:151], v[88:91]
	v_mfma_f32_16x16x32_bf16 v[92:95], v[192:195], v[148:151], v[92:95]
	ds_read_b128 v[136:139], v157 offset:0
	ds_read_b128 v[140:143], v157 offset:2048
	ds_read_b128 v[144:147], v157 offset:4096
	s_waitcnt lgkmcnt(3)
	v_mfma_f32_16x16x32_bf16 v[96:99], v[184:187], v[164:167], v[96:99]
	v_mfma_f32_16x16x32_bf16 v[100:103], v[192:195], v[164:167], v[100:103]
	v_mfma_f32_16x16x32_bf16 v[104:107], v[184:187], v[168:171], v[104:107]
	v_mfma_f32_16x16x32_bf16 v[108:111], v[192:195], v[168:171], v[108:111]
	v_mfma_f32_16x16x32_bf16 v[112:115], v[184:187], v[172:175], v[112:115]
	v_mfma_f32_16x16x32_bf16 v[116:119], v[192:195], v[172:175], v[116:119]
	v_mfma_f32_16x16x32_bf16 v[120:123], v[184:187], v[176:179], v[120:123]
	v_mfma_f32_16x16x32_bf16 v[124:127], v[192:195], v[176:179], v[124:127]
	ds_read_b128 v[164:167], v157 offset:6144
	ds_read_b128 v[168:171], v157 offset:8192
	ds_read_b128 v[172:175], v157 offset:10240
	s_waitcnt lgkmcnt(3)
	v_mfma_f32_16x16x32_bf16 v[0:3], v[188:191], v[136:139], v[0:3]
	v_mfma_f32_16x16x32_bf16 v[4:7], v[196:199], v[136:139], v[4:7]
	v_mfma_f32_16x16x32_bf16 v[8:11], v[188:191], v[140:143], v[8:11]
	v_mfma_f32_16x16x32_bf16 v[12:15], v[196:199], v[140:143], v[12:15]
	v_mfma_f32_16x16x32_bf16 v[16:19], v[188:191], v[144:147], v[16:19]
	v_mfma_f32_16x16x32_bf16 v[20:23], v[196:199], v[144:147], v[20:23]
	ds_read_b128 v[136:139], v157 offset:12288
	ds_read_b128 v[140:143], v157 offset:14336
	ds_read_b128 v[144:147], v157 offset:16384
	ds_read_b128 v[148:151], v157 offset:18432
	ds_read_b128 v[152:155], v157 offset:20480
	s_waitcnt lgkmcnt(5)
	v_mfma_f32_16x16x32_bf16 v[24:27], v[188:191], v[164:167], v[24:27]
	v_mfma_f32_16x16x32_bf16 v[28:31], v[196:199], v[164:167], v[28:31]
	v_mfma_f32_16x16x32_bf16 v[32:35], v[188:191], v[168:171], v[32:35]
	v_mfma_f32_16x16x32_bf16 v[36:39], v[196:199], v[168:171], v[36:39]
	v_mfma_f32_16x16x32_bf16 v[40:43], v[188:191], v[172:175], v[40:43]
	v_mfma_f32_16x16x32_bf16 v[44:47], v[196:199], v[172:175], v[44:47]
	ds_read_b128 v[164:167], v157 offset:22528
	ds_read_b128 v[168:171], v157 offset:24576
	ds_read_b128 v[172:175], v157 offset:26624
	ds_read_b128 v[176:179], v157 offset:28672
	ds_read_b128 v[180:183], v157 offset:30720
	s_waitcnt lgkmcnt(5)
	v_mfma_f32_16x16x32_bf16 v[48:51], v[188:191], v[136:139], v[48:51]
	v_mfma_f32_16x16x32_bf16 v[52:55], v[196:199], v[136:139], v[52:55]
	v_mfma_f32_16x16x32_bf16 v[56:59], v[188:191], v[140:143], v[56:59]
	v_mfma_f32_16x16x32_bf16 v[60:63], v[196:199], v[140:143], v[60:63]
	v_mfma_f32_16x16x32_bf16 v[64:67], v[188:191], v[144:147], v[64:67]
	v_mfma_f32_16x16x32_bf16 v[68:71], v[196:199], v[144:147], v[68:71]
	v_mfma_f32_16x16x32_bf16 v[72:75], v[188:191], v[148:151], v[72:75]
	v_mfma_f32_16x16x32_bf16 v[76:79], v[196:199], v[148:151], v[76:79]
	v_mfma_f32_16x16x32_bf16 v[80:83], v[188:191], v[152:155], v[80:83]
	v_mfma_f32_16x16x32_bf16 v[84:87], v[196:199], v[152:155], v[84:87]
	s_waitcnt vmcnt(0) lgkmcnt(0)
	s_barrier
	ds_read_b128 v[136:139], v158 offset:0
	ds_read_b128 v[140:143], v158 offset:2048
	ds_read_b128 v[144:147], v158 offset:4096
	ds_read_b128 v[148:151], v158 offset:6144
	s_cmp_ge_u32 s63, 2
	s_cbranch_scc1 .Lg2_up_nd16_0
	s_add_u32 s56, s56, 0x80
	s_addc_u32 s57, s57, 0
	s_add_u32 m0, s62, 0x0
	s_add_u32 s4, s56, 0x0
	s_addc_u32 s5, s57, 0
	global_load_lds_dwordx4 v162, s[4:5]
	s_add_u32 m0, s62, 0x1000
	s_add_u32 s4, s56, 0x72000
	s_addc_u32 s5, s57, 0
	global_load_lds_dwordx4 v162, s[4:5]
	s_add_u32 m0, s62, 0x2000
	s_add_u32 s4, s56, 0xe4000
	s_addc_u32 s5, s57, 0
	global_load_lds_dwordx4 v162, s[4:5]
	s_add_u32 m0, s62, 0x3000
	s_add_u32 s4, s56, 0x156000
	s_addc_u32 s5, s57, 0
	global_load_lds_dwordx4 v162, s[4:5]
	s_add_u32 m0, s62, 0x4000
	s_add_u32 s4, s56, 0x1c8000
	s_addc_u32 s5, s57, 0
	global_load_lds_dwordx4 v162, s[4:5]
	s_add_u32 m0, s62, 0x5000
	s_add_u32 s4, s56, 0x23a000
	s_addc_u32 s5, s57, 0
	global_load_lds_dwordx4 v162, s[4:5]
	s_add_u32 m0, s62, 0x6000
	s_add_u32 s4, s56, 0x2ac000
	s_addc_u32 s5, s57, 0
	global_load_lds_dwordx4 v162, s[4:5]
	s_add_u32 m0, s62, 0x7000
	s_add_u32 s4, s56, 0x31e000
	s_addc_u32 s5, s57, 0
	global_load_lds_dwordx4 v162, s[4:5]
.Lg2_up_nd16_0:
	v_mfma_f32_16x16x32_bf16 v[88:91], v[188:191], v[164:167], v[88:91]
	v_mfma_f32_16x16x32_bf16 v[92:95], v[196:199], v[164:167], v[92:95]
	v_mfma_f32_16x16x32_bf16 v[96:99], v[188:191], v[168:171], v[96:99]
	v_mfma_f32_16x16x32_bf16 v[100:103], v[196:199], v[168:171], v[100:103]
	v_mfma_f32_16x16x32_bf16 v[104:107], v[188:191], v[172:175], v[104:107]
	v_mfma_f32_16x16x32_bf16 v[108:111], v[196:199], v[172:175], v[108:111]
	v_mfma_f32_16x16x32_bf16 v[112:115], v[188:191], v[176:179], v[112:115]
	v_mfma_f32_16x16x32_bf16 v[116:119], v[196:199], v[176:179], v[116:119]
	v_mfma_f32_16x16x32_bf16 v[120:123], v[188:191], v[180:183], v[120:123]
	v_mfma_f32_16x16x32_bf16 v[124:127], v[196:199], v[180:183], v[124:127]
	s_cmp_ge_u32 s63, 2
	s_cbranch_scc1 .Lg2_up_nb16_1
	s_add_u32 s58, s58, 0x800
	s_addc_u32 s59, s59, 0
	global_load_dwordx4 v[184:187], v160, s[58:59] offset:0
	global_load_dwordx4 v[188:191], v160, s[58:59] offset:1024
	global_load_dwordx4 v[192:195], v161, s[58:59] offset:0
	global_load_dwordx4 v[196:199], v161, s[58:59] offset:1024
.Lg2_up_nb16_1:
	ds_read_b128 v[164:167], v158 offset:8192
	ds_read_b128 v[168:171], v158 offset:10240
	ds_read_b128 v[172:175], v158 offset:12288
	ds_read_b128 v[176:179], v158 offset:14336
	s_waitcnt lgkmcnt(4)
	v_mfma_f32_16x16x32_bf16 v[0:3], v[200:203], v[136:139], v[0:3]
	v_mfma_f32_16x16x32_bf16 v[4:7], v[208:211], v[136:139], v[4:7]
	v_mfma_f32_16x16x32_bf16 v[8:11], v[200:203], v[140:143], v[8:11]
	v_mfma_f32_16x16x32_bf16 v[12:15], v[208:211], v[140:143], v[12:15]
	v_mfma_f32_16x16x32_bf16 v[16:19], v[200:203], v[144:147], v[16:19]
	v_mfma_f32_16x16x32_bf16 v[20:23], v[208:211], v[144:147], v[20:23]
	v_mfma_f32_16x16x32_bf16 v[24:27], v[200:203], v[148:151], v[24:27]
	v_mfma_f32_16x16x32_bf16 v[28:31], v[208:211], v[148:151], v[28:31]
	ds_read_b128 v[136:139], v158 offset:16384
	ds_read_b128 v[140:143], v158 offset:18432
	ds_read_b128 v[144:147], v158 offset:20480
	ds_read_b128 v[148:151], v158 offset:22528
	s_waitcnt lgkmcnt(4)
	v_mfma_f32_16x16x32_bf16 v[32:35], v[200:203], v[164:167], v[32:35]
	v_mfma_f32_16x16x32_bf16 v[36:39], v[208:211], v[164:167], v[36:39]
	v_mfma_f32_16x16x32_bf16 v[40:43], v[200:203], v[168:171], v[40:43]
	v_mfma_f32_16x16x32_bf16 v[44:47], v[208:211], v[168:171], v[44:47]
	v_mfma_f32_16x16x32_bf16 v[48:51], v[200:203], v[172:175], v[48:51]
	v_mfma_f32_16x16x32_bf16 v[52:55], v[208:211], v[172:175], v[52:55]
	v_mfma_f32_16x16x32_bf16 v[56:59], v[200:203], v[176:179], v[56:59]
	v_mfma_f32_16x16x32_bf16 v[60:63], v[208:211], v[176:179], v[60:63]
	ds_read_b128 v[164:167], v158 offset:24576
	ds_read_b128 v[168:171], v158 offset:26624
	ds_read_b128 v[172:175], v158 offset:28672
	ds_read_b128 v[176:179], v158 offset:30720
	s_waitcnt lgkmcnt(4)
	v_mfma_f32_16x16x32_bf16 v[64:67], v[200:203], v[136:139], v[64:67]
	v_mfma_f32_16x16x32_bf16 v[68:71], v[208:211], v[136:139], v[68:71]
	v_mfma_f32_16x16x32_bf16 v[72:75], v[200:203], v[140:143], v[72:75]
	v_mfma_f32_16x16x32_bf16 v[76:79], v[208:211], v[140:143], v[76:79]
	v_mfma_f32_16x16x32_bf16 v[80:83], v[200:203], v[144:147], v[80:83]
	v_mfma_f32_16x16x32_bf16 v[84:87], v[208:211], v[144:147], v[84:87]
	v_mfma_f32_16x16x32_bf16 v[88:91], v[200:203], v[148:151], v[88:91]
	v_mfma_f32_16x16x32_bf16 v[92:95], v[208:211], v[148:151], v[92:95]
	ds_read_b128 v[136:139], v159 offset:0
	ds_read_b128 v[140:143], v159 offset:2048
	ds_read_b128 v[144:147], v159 offset:4096
	s_waitcnt lgkmcnt(3)
	v_mfma_f32_16x16x32_bf16 v[96:99], v[200:203], v[164:167], v[96:99]
	v_mfma_f32_16x16x32_bf16 v[100:103], v[208:211], v[164:167], v[100:103]
	v_mfma_f32_16x16x32_bf16 v[104:107], v[200:203], v[168:171], v[104:107]
	v_mfma_f32_16x16x32_bf16 v[108:111], v[208:211], v[168:171], v[108:111]
	v_mfma_f32_16x16x32_bf16 v[112:115], v[200:203], v[172:175], v[112:115]
	v_mfma_f32_16x16x32_bf16 v[116:119], v[208:211], v[172:175], v[116:119]
	v_mfma_f32_16x16x32_bf16 v[120:123], v[200:203], v[176:179], v[120:123]
	v_mfma_f32_16x16x32_bf16 v[124:127], v[208:211], v[176:179], v[124:127]
	ds_read_b128 v[164:167], v159 offset:6144
	ds_read_b128 v[168:171], v159 offset:8192
	ds_read_b128 v[172:175], v159 offset:10240
	s_waitcnt lgkmcnt(3)
	v_mfma_f32_16x16x32_bf16 v[0:3], v[204:207], v[136:139], v[0:3]
	v_mfma_f32_16x16x32_bf16 v[4:7], v[240:243], v[136:139], v[4:7]
	v_mfma_f32_16x16x32_bf16 v[8:11], v[204:207], v[140:143], v[8:11]
	v_mfma_f32_16x16x32_bf16 v[12:15], v[240:243], v[140:143], v[12:15]
	v_mfma_f32_16x16x32_bf16 v[16:19], v[204:207], v[144:147], v[16:19]
	v_mfma_f32_16x16x32_bf16 v[20:23], v[240:243], v[144:147], v[20:23]
	ds_read_b128 v[136:139], v159 offset:12288
	ds_read_b128 v[140:143], v159 offset:14336
	ds_read_b128 v[144:147], v159 offset:16384
	ds_read_b128 v[148:151], v159 offset:18432
	ds_read_b128 v[152:155], v159 offset:20480
	s_waitcnt lgkmcnt(5)
	v_mfma_f32_16x16x32_bf16 v[24:27], v[204:207], v[164:167], v[24:27]
	v_mfma_f32_16x16x32_bf16 v[28:31], v[240:243], v[164:167], v[28:31]
	v_mfma_f32_16x16x32_bf16 v[32:35], v[204:207], v[168:171], v[32:35]
	v_mfma_f32_16x16x32_bf16 v[36:39], v[240:243], v[168:171], v[36:39]
	v_mfma_f32_16x16x32_bf16 v[40:43], v[204:207], v[172:175], v[40:43]
	v_mfma_f32_16x16x32_bf16 v[44:47], v[240:243], v[172:175], v[44:47]
	ds_read_b128 v[164:167], v159 offset:22528
	ds_read_b128 v[168:171], v159 offset:24576
	ds_read_b128 v[172:175], v159 offset:26624
	ds_read_b128 v[176:179], v159 offset:28672
	ds_read_b128 v[180:183], v159 offset:30720
	s_waitcnt lgkmcnt(5)
	v_mfma_f32_16x16x32_bf16 v[48:51], v[204:207], v[136:139], v[48:51]
	v_mfma_f32_16x16x32_bf16 v[52:55], v[240:243], v[136:139], v[52:55]
	v_mfma_f32_16x16x32_bf16 v[56:59], v[204:207], v[140:143], v[56:59]
	v_mfma_f32_16x16x32_bf16 v[60:63], v[240:243], v[140:143], v[60:63]
	v_mfma_f32_16x16x32_bf16 v[64:67], v[204:207], v[144:147], v[64:67]
	v_mfma_f32_16x16x32_bf16 v[68:71], v[240:243], v[144:147], v[68:71]
	v_mfma_f32_16x16x32_bf16 v[72:75], v[204:207], v[148:151], v[72:75]
	v_mfma_f32_16x16x32_bf16 v[76:79], v[240:243], v[148:151], v[76:79]
	v_mfma_f32_16x16x32_bf16 v[80:83], v[204:207], v[152:155], v[80:83]
	v_mfma_f32_16x16x32_bf16 v[84:87], v[240:243], v[152:155], v[84:87]
	s_waitcnt vmcnt(0) lgkmcnt(0)
	s_barrier
	s_cmp_ge_u32 s63, 2
	s_cbranch_scc1 .Lg2_up_nd16_1
	ds_read_b128 v[136:139], v156 offset:0
	ds_read_b128 v[140:143], v156 offset:2048
	ds_read_b128 v[144:147], v156 offset:4096
	ds_read_b128 v[148:151], v156 offset:6144
	s_add_u32 s56, s56, 0x80
	s_addc_u32 s57, s57, 0
	s_add_u32 m0, s62, 0x8800
	s_add_u32 s4, s56, 0x0
	s_addc_u32 s5, s57, 0
	global_load_lds_dwordx4 v162, s[4:5]
	s_add_u32 m0, s62, 0x9800
	s_add_u32 s4, s56, 0x72000
	s_addc_u32 s5, s57, 0
	global_load_lds_dwordx4 v162, s[4:5]
	s_add_u32 m0, s62, 0xa800
	s_add_u32 s4, s56, 0xe4000
	s_addc_u32 s5, s57, 0
	global_load_lds_dwordx4 v162, s[4:5]
	s_add_u32 m0, s62, 0xb800
	s_add_u32 s4, s56, 0x156000
	s_addc_u32 s5, s57, 0
	global_load_lds_dwordx4 v162, s[4:5]
	s_add_u32 m0, s62, 0xc800
	s_add_u32 s4, s56, 0x1c8000
	s_addc_u32 s5, s57, 0
	global_load_lds_dwordx4 v162, s[4:5]
	s_add_u32 m0, s62, 0xd800
	s_add_u32 s4, s56, 0x23a000
	s_addc_u32 s5, s57, 0
	global_load_lds_dwordx4 v162, s[4:5]
	s_add_u32 m0, s62, 0xe800
	s_add_u32 s4, s56, 0x2ac000
	s_addc_u32 s5, s57, 0
	global_load_lds_dwordx4 v162, s[4:5]
	s_add_u32 m0, s62, 0xf800
	s_add_u32 s4, s56, 0x31e000
	s_addc_u32 s5, s57, 0
	global_load_lds_dwordx4 v162, s[4:5]
